# GEMM K-loops: LDS-DMA issue spread over the first two MFMA groups
# speedup vs baseline: 1.0876x; 1.0057x over previous
.LBB0_212:
	s_add_i32 s1, s0, 0x10000
	s_and_b32 s11, s1, 0x10000
	s_waitcnt vmcnt(0)
	s_barrier
	s_and_b32 s0, s0, 0x10000
	s_add_i32 s0, s0, 0
	v_add_u32_e32 v155, s0, v153
	v_add_u32_e32 v164, v155, v151
	ds_read_b128 v[156:159], v164
	ds_read_b128 v[160:163], v164 offset:2048
	ds_read_b128 v[178:181], v164 offset:4096
	ds_read_b128 v[182:185], v164 offset:6144
	v_add_u32_e32 v249, v155, v150
	v_add_u32_e32 v164, s0, v154
	v_add_u32_e32 v165, v164, v151
	ds_read_b128 v[186:189], v165 offset:32768
	ds_read_b128 v[192:195], v165 offset:34816
	ds_read_b128 v[198:201], v165 offset:36864
	ds_read_b128 v[204:207], v165 offset:38912
	v_add_u32_e32 v248, v164, v150
	ds_read_b128 v[224:227], v165 offset:40960
	ds_read_b128 v[228:231], v165 offset:43008
	ds_read_b128 v[232:235], v165 offset:45056
	ds_read_b128 v[236:239], v165 offset:47104
	v_add_u32_e32 v251, s11, v152
	v_add_u32_e32 v240, 0x2000, v251
	v_readfirstlane_b32 s11, v251
	v_lshl_add_u64 v[174:175], v[144:145], 0, s[8:9]
	s_mov_b32 m0, s11
	v_readfirstlane_b32 s11, v240
	v_add_u32_e32 v240, 0x4000, v251
	global_load_lds_dwordx4 v[174:175], off
	v_lshl_add_u64 v[174:175], v[134:135], 0, s[8:9]
	s_mov_b32 m0, s11
	s_waitcnt lgkmcnt(4)
	v_mfma_f32_16x16x32_bf16 v[124:127], v[156:159], v[186:189], v[124:127]
	ds_read_b128 v[208:211], v249
	v_mfma_f32_16x16x32_bf16 v[120:123], v[156:159], v[192:195], v[120:123]
	ds_read_b128 v[212:215], v249 offset:2048
	v_readfirstlane_b32 s11, v240
	v_add_u32_e32 v240, 0x6000, v251
	v_mfma_f32_16x16x32_bf16 v[116:119], v[156:159], v[198:201], v[116:119]
	ds_read_b128 v[216:219], v249 offset:4096
	global_load_lds_dwordx4 v[174:175], off
	v_lshl_add_u64 v[174:175], v[132:133], 0, s[8:9]
	v_mfma_f32_16x16x32_bf16 v[112:115], v[156:159], v[204:207], v[112:115]
	ds_read_b128 v[220:223], v249 offset:6144
	s_mov_b32 m0, s11
	v_readfirstlane_b32 s11, v240
	v_mfma_f32_16x16x32_bf16 v[104:107], v[160:163], v[186:189], v[104:107]
	global_load_lds_dwordx4 v[174:175], off
	v_lshl_add_u64 v[174:175], v[130:131], 0, s[8:9]
	v_mfma_f32_16x16x32_bf16 v[96:99], v[160:163], v[192:195], v[96:99]
	s_mov_b32 m0, s11
	v_add_u32_e32 v250, 0x8000, v251
	v_mfma_f32_16x16x32_bf16 v[88:91], v[160:163], v[198:201], v[88:91]
	global_load_lds_dwordx4 v[174:175], off
	v_lshl_add_u64 v[174:175], v[128:129], 0, s[8:9]
	v_mfma_f32_16x16x32_bf16 v[80:83], v[160:163], v[204:207], v[80:83]
	v_readfirstlane_b32 s11, v250
	v_add_u32_e32 v250, 0xa000, v251
	v_mfma_f32_16x16x32_bf16 v[72:75], v[178:181], v[186:189], v[72:75]
	v_lshl_add_u64 v[240:241], v[174:175], 0, s[66:67]
	s_mov_b32 m0, s11
	v_mfma_f32_16x16x32_bf16 v[64:67], v[178:181], v[192:195], v[64:67]
	s_mov_b64 s[12:13], 0x22080
	v_readfirstlane_b32 s11, v250
	v_mfma_f32_16x16x32_bf16 v[56:59], v[178:181], v[198:201], v[56:59]
	v_add_u32_e32 v250, 0xc000, v251
	global_load_lds_dwordx4 v[240:241], off
	v_mfma_f32_16x16x32_bf16 v[48:51], v[178:181], v[204:207], v[48:51]
	v_lshl_add_u64 v[240:241], v[174:175], 0, s[12:13]
	s_mov_b32 m0, s11
	v_mfma_f32_16x16x32_bf16 v[40:43], v[182:185], v[186:189], v[40:43]
	s_mov_b64 s[12:13], 0x44080
	v_readfirstlane_b32 s11, v250
	v_mfma_f32_16x16x32_bf16 v[32:35], v[182:185], v[192:195], v[32:35]
	v_add_u32_e32 v251, 0xe000, v251
	global_load_lds_dwordx4 v[240:241], off
	v_mfma_f32_16x16x32_bf16 v[24:27], v[182:185], v[198:201], v[24:27]
	v_lshl_add_u64 v[240:241], v[174:175], 0, s[12:13]
	s_mov_b32 m0, s11
	v_mfma_f32_16x16x32_bf16 v[16:19], v[182:185], v[204:207], v[16:19]
	s_mov_b64 s[12:13], 0x66080
	v_readfirstlane_b32 s11, v251
	s_waitcnt lgkmcnt(4)
	v_mfma_f32_16x16x32_bf16 v[100:103], v[156:159], v[224:227], v[100:103]
	global_load_lds_dwordx4 v[240:241], off
	v_lshl_add_u64 v[174:175], v[174:175], 0, s[12:13]
	v_mfma_f32_16x16x32_bf16 v[92:95], v[156:159], v[228:231], v[92:95]
	s_mov_b32 m0, s11
	global_load_lds_dwordx4 v[174:175], off
	v_mfma_f32_16x16x32_bf16 v[84:87], v[156:159], v[232:235], v[84:87]
	ds_read_b128 v[186:189], v248 offset:32768
	v_mfma_f32_16x16x32_bf16 v[76:79], v[156:159], v[236:239], v[76:79]
	ds_read_b128 v[192:195], v248 offset:34816
	v_mfma_f32_16x16x32_bf16 v[68:71], v[160:163], v[224:227], v[68:71]
	ds_read_b128 v[198:201], v248 offset:36864
	v_mfma_f32_16x16x32_bf16 v[60:63], v[160:163], v[228:231], v[60:63]
	ds_read_b128 v[204:207], v248 offset:38912
	v_mfma_f32_16x16x32_bf16 v[52:55], v[160:163], v[232:235], v[52:55]
	v_mfma_f32_16x16x32_bf16 v[44:47], v[160:163], v[236:239], v[44:47]
	v_mfma_f32_16x16x32_bf16 v[36:39], v[178:181], v[224:227], v[36:39]
	v_mfma_f32_16x16x32_bf16 v[28:31], v[178:181], v[228:231], v[28:31]
	v_mfma_f32_16x16x32_bf16 v[20:23], v[178:181], v[232:235], v[20:23]
	v_mfma_f32_16x16x32_bf16 v[12:15], v[178:181], v[236:239], v[12:15]
	v_mfma_f32_16x16x32_bf16 v[8:11], v[182:185], v[224:227], v[8:11]
	v_mfma_f32_16x16x32_bf16 v[4:7], v[182:185], v[228:231], v[4:7]
	v_mfma_f32_16x16x32_bf16 v[0:3], v[182:185], v[232:235], v[0:3]
	v_mfma_f32_16x16x32_bf16 v[108:111], v[182:185], v[236:239], v[108:111]
	s_waitcnt lgkmcnt(0)
	v_mfma_f32_16x16x32_bf16 v[124:127], v[208:211], v[186:189], v[124:127]
	ds_read_b128 v[224:227], v248 offset:40960
	v_mfma_f32_16x16x32_bf16 v[120:123], v[208:211], v[192:195], v[120:123]
	ds_read_b128 v[228:231], v248 offset:43008
	v_mfma_f32_16x16x32_bf16 v[116:119], v[208:211], v[198:201], v[116:119]
	ds_read_b128 v[232:235], v248 offset:45056
	v_mfma_f32_16x16x32_bf16 v[112:115], v[208:211], v[204:207], v[112:115]
	ds_read_b128 v[236:239], v248 offset:47104
	v_mfma_f32_16x16x32_bf16 v[104:107], v[212:215], v[186:189], v[104:107]
	v_mfma_f32_16x16x32_bf16 v[96:99], v[212:215], v[192:195], v[96:99]
	v_mfma_f32_16x16x32_bf16 v[88:91], v[212:215], v[198:201], v[88:91]
	v_mfma_f32_16x16x32_bf16 v[80:83], v[212:215], v[204:207], v[80:83]
	v_mfma_f32_16x16x32_bf16 v[72:75], v[216:219], v[186:189], v[72:75]
	v_mfma_f32_16x16x32_bf16 v[64:67], v[216:219], v[192:195], v[64:67]
	v_mfma_f32_16x16x32_bf16 v[56:59], v[216:219], v[198:201], v[56:59]
	v_mfma_f32_16x16x32_bf16 v[48:51], v[216:219], v[204:207], v[48:51]
	v_mfma_f32_16x16x32_bf16 v[40:43], v[220:223], v[186:189], v[40:43]
	v_mfma_f32_16x16x32_bf16 v[32:35], v[220:223], v[192:195], v[32:35]
	v_mfma_f32_16x16x32_bf16 v[24:27], v[220:223], v[198:201], v[24:27]
	v_mfma_f32_16x16x32_bf16 v[16:19], v[220:223], v[204:207], v[16:19]
	s_waitcnt lgkmcnt(0)
	v_mfma_f32_16x16x32_bf16 v[100:103], v[208:211], v[224:227], v[100:103]
	v_mfma_f32_16x16x32_bf16 v[92:95], v[208:211], v[228:231], v[92:95]
	v_mfma_f32_16x16x32_bf16 v[84:87], v[208:211], v[232:235], v[84:87]
	v_mfma_f32_16x16x32_bf16 v[76:79], v[208:211], v[236:239], v[76:79]
	v_mfma_f32_16x16x32_bf16 v[68:71], v[212:215], v[224:227], v[68:71]
	v_mfma_f32_16x16x32_bf16 v[60:63], v[212:215], v[228:231], v[60:63]
	v_mfma_f32_16x16x32_bf16 v[52:55], v[212:215], v[232:235], v[52:55]
	v_mfma_f32_16x16x32_bf16 v[44:47], v[212:215], v[236:239], v[44:47]
	v_mfma_f32_16x16x32_bf16 v[36:39], v[216:219], v[224:227], v[36:39]
	v_mfma_f32_16x16x32_bf16 v[28:31], v[216:219], v[228:231], v[28:31]
	v_mfma_f32_16x16x32_bf16 v[20:23], v[216:219], v[232:235], v[20:23]
	v_mfma_f32_16x16x32_bf16 v[12:15], v[216:219], v[236:239], v[12:15]
	s_add_u32 s8, s8, 0x80
	s_addc_u32 s9, s9, 0
	s_cmpk_eq_i32 s8, 0x780
	s_mov_b32 s0, s1
	v_mfma_f32_16x16x32_bf16 v[8:11], v[220:223], v[224:227], v[8:11]
	v_mfma_f32_16x16x32_bf16 v[4:7], v[220:223], v[228:231], v[4:7]
	v_mfma_f32_16x16x32_bf16 v[0:3], v[220:223], v[232:235], v[0:3]
	v_mfma_f32_16x16x32_bf16 v[108:111], v[220:223], v[236:239], v[108:111]
	s_cbranch_scc0 .LBB0_212
	s_add_i32 s0, 0, 0x10000
	v_add_u32_e32 v144, s0, v154
	v_add_u32_e32 v162, s0, v153
	v_add_u32_e32 v145, v144, v151
	v_add_u32_e32 v151, v162, v151
	s_waitcnt vmcnt(0)
	s_barrier
	ds_read_b128 v[128:131], v145 offset:38912
	ds_read_b128 v[132:135], v145 offset:36864
	ds_read_b128 v[154:157], v145 offset:34816
	ds_read_b128 v[158:161], v145 offset:32768
	ds_read_b128 v[178:181], v151 offset:6144
	ds_read_b128 v[182:185], v151 offset:4096
	ds_read_b128 v[186:189], v151 offset:2048
	ds_read_b128 v[204:207], v151
	s_waitcnt lgkmcnt(0)
	v_mfma_f32_16x16x32_bf16 v[124:127], v[204:207], v[158:161], v[124:127]
	v_mfma_f32_16x16x32_bf16 v[120:123], v[204:207], v[154:157], v[120:123]
	v_mfma_f32_16x16x32_bf16 v[116:119], v[204:207], v[132:135], v[116:119]
	v_mfma_f32_16x16x32_bf16 v[112:115], v[204:207], v[128:131], v[112:115]
	v_mfma_f32_16x16x32_bf16 v[104:107], v[186:189], v[158:161], v[104:107]
	v_mfma_f32_16x16x32_bf16 v[72:75], v[182:185], v[158:161], v[72:75]
	v_mfma_f32_16x16x32_bf16 v[64:67], v[182:185], v[154:157], v[64:67]
	v_mfma_f32_16x16x32_bf16 v[56:59], v[182:185], v[132:135], v[56:59]
	v_mfma_f32_16x16x32_bf16 v[48:51], v[182:185], v[128:131], v[48:51]
	v_mfma_f32_16x16x32_bf16 v[208:211], v[186:189], v[154:157], v[96:99]
	v_mfma_f32_16x16x32_bf16 v[212:215], v[186:189], v[132:135], v[88:91]
	v_mfma_f32_16x16x32_bf16 v[216:219], v[186:189], v[128:131], v[80:83]
	v_mfma_f32_16x16x32_bf16 v[158:161], v[178:181], v[158:161], v[40:43]
	v_mfma_f32_16x16x32_bf16 v[152:155], v[178:181], v[154:157], v[32:35]
	v_mfma_f32_16x16x32_bf16 v[132:135], v[178:181], v[132:135], v[24:27]
	v_mfma_f32_16x16x32_bf16 v[128:131], v[178:181], v[128:131], v[16:19]
	s_nop 2
	ds_read_b128 v[16:19], v145 offset:40960
	ds_read_b128 v[24:27], v145 offset:43008
	ds_read_b128 v[32:35], v145 offset:45056
	ds_read_b128 v[40:43], v145 offset:47104
	s_waitcnt lgkmcnt(0)
	v_mfma_f32_16x16x32_bf16 v[100:103], v[204:207], v[16:19], v[100:103]
	v_mfma_f32_16x16x32_bf16 v[92:95], v[204:207], v[24:27], v[92:95]
	v_mfma_f32_16x16x32_bf16 v[220:223], v[204:207], v[32:35], v[84:87]
	v_mfma_f32_16x16x32_bf16 v[76:79], v[204:207], v[40:43], v[76:79]
	v_mfma_f32_16x16x32_bf16 v[68:71], v[186:189], v[16:19], v[68:71]
	v_mfma_f32_16x16x32_bf16 v[60:63], v[186:189], v[24:27], v[60:63]
	v_mfma_f32_16x16x32_bf16 v[204:207], v[186:189], v[32:35], v[52:55]
	v_mfma_f32_16x16x32_bf16 v[44:47], v[186:189], v[40:43], v[44:47]
	v_mfma_f32_16x16x32_bf16 v[186:189], v[182:185], v[16:19], v[36:39]
	v_mfma_f32_16x16x32_bf16 v[224:227], v[182:185], v[24:27], v[28:31]
	v_mfma_f32_16x16x32_bf16 v[228:231], v[182:185], v[32:35], v[20:23]
	v_mfma_f32_16x16x32_bf16 v[182:185], v[182:185], v[40:43], v[12:15]
	v_mfma_f32_16x16x32_bf16 v[232:235], v[178:181], v[16:19], v[8:11]
	v_mfma_f32_16x16x32_bf16 v[236:239], v[178:181], v[24:27], v[4:7]
	v_mfma_f32_16x16x32_bf16 v[240:243], v[178:181], v[32:35], v[0:3]
	v_mfma_f32_16x16x32_bf16 v[244:247], v[178:181], v[40:43], v[108:111]
	s_nop 1
	v_add_u32_e32 v0, v162, v150
	v_add_u32_e32 v144, v144, v150
	ds_read_b128 v[108:111], v0
	ds_read_b128 v[178:181], v0 offset:2048
	ds_read_b128 v[248:251], v0 offset:4096
	ds_read_b128 v[192:195], v0 offset:6144
	ds_read_b128 v[0:3], v144 offset:32768
	ds_read_b128 v[4:7], v144 offset:34816
	ds_read_b128 v[198:201], v144 offset:36864
	ds_read_b128 v[162:165], v144 offset:38912
	s_waitcnt lgkmcnt(0)
	v_mfma_f32_16x16x32_bf16 v[88:91], v[108:111], v[0:3], v[124:127]
	v_mfma_f32_16x16x32_bf16 v[96:99], v[108:111], v[4:7], v[120:123]
	v_mfma_f32_16x16x32_bf16 v[80:83], v[108:111], v[198:201], v[116:119]
	v_mfma_f32_16x16x32_bf16 v[84:87], v[108:111], v[162:165], v[112:115]
	v_mfma_f32_16x16x32_bf16 v[40:43], v[178:181], v[0:3], v[104:107]
	v_mfma_f32_16x16x32_bf16 v[52:55], v[178:181], v[4:7], v[208:211]
	v_mfma_f32_16x16x32_bf16 v[32:35], v[178:181], v[198:201], v[212:215]
	v_mfma_f32_16x16x32_bf16 v[36:39], v[178:181], v[162:165], v[216:219]
	v_mfma_f32_16x16x32_bf16 v[24:27], v[248:251], v[0:3], v[72:75]
	v_mfma_f32_16x16x32_bf16 v[28:31], v[248:251], v[4:7], v[64:67]
	v_mfma_f32_16x16x32_bf16 v[16:19], v[248:251], v[198:201], v[56:59]
	v_mfma_f32_16x16x32_bf16 v[20:23], v[248:251], v[162:165], v[48:51]
	v_mfma_f32_16x16x32_bf16 v[8:11], v[192:195], v[0:3], v[158:161]
	v_mfma_f32_16x16x32_bf16 v[12:15], v[192:195], v[4:7], v[152:155]
	v_mfma_f32_16x16x32_bf16 v[0:3], v[192:195], v[198:201], v[132:135]
	v_mfma_f32_16x16x32_bf16 v[4:7], v[192:195], v[162:165], v[128:131]
	ds_read_b128 v[48:51], v144 offset:40960
	ds_read_b128 v[64:67], v144 offset:43008
	s_nop 0
	ds_read_b128 v[128:131], v144 offset:45056
	ds_read_b128 v[132:135], v144 offset:47104
	s_waitcnt lgkmcnt(0)
	v_mfma_f32_16x16x32_bf16 v[104:107], v[178:181], v[48:51], v[68:71]
	v_cmp_ne_u32_e64 s[8:9], 0, v146
	v_cmp_eq_u32_e32 vcc, 0, v146
	s_waitcnt vmcnt(0)
	v_lshl_or_b32 v68, v148, 2, v149
	v_lshl_add_u32 v69, v147, 2, 0
	v_mfma_f32_16x16x32_bf16 v[120:123], v[108:111], v[48:51], v[100:103]
	s_barrier
	v_mfma_f32_16x16x32_bf16 v[124:127], v[108:111], v[64:67], v[92:95]
	v_mfma_f32_16x16x32_bf16 v[112:115], v[108:111], v[128:131], v[220:223]
	v_mfma_f32_16x16x32_bf16 v[116:119], v[108:111], v[132:135], v[76:79]
	v_mfma_f32_16x16x32_bf16 v[108:111], v[178:181], v[64:67], v[60:63]
	v_mfma_f32_16x16x32_bf16 v[92:95], v[178:181], v[128:131], v[204:207]
	v_mfma_f32_16x16x32_bf16 v[100:103], v[178:181], v[132:135], v[44:47]
	v_mfma_f32_16x16x32_bf16 v[56:59], v[248:251], v[48:51], v[186:189]
	v_mfma_f32_16x16x32_bf16 v[60:63], v[248:251], v[64:67], v[224:227]
	v_mfma_f32_16x16x32_bf16 v[44:47], v[248:251], v[128:131], v[228:231]
	v_mfma_f32_16x16x32_bf16 v[72:75], v[248:251], v[132:135], v[182:185]
	v_mfma_f32_16x16x32_bf16 v[48:51], v[192:195], v[48:51], v[232:235]
	s_nop 1
	v_lshl_add_u32 v182, v68, 9, v69
	v_add_u32_e32 v183, 0x400, v182
	v_add_u32_e32 v181, 0x2000, v182
	v_mfma_f32_16x16x32_bf16 v[64:67], v[192:195], v[64:67], v[236:239]
	v_add_u32_e32 v180, 0x2400, v182
	v_add_u32_e32 v179, 0x4000, v182
	v_add_u32_e32 v178, 0x4400, v182
	v_mfma_f32_16x16x32_bf16 v[68:71], v[192:195], v[128:131], v[240:243]
	v_add_u32_e32 v175, 0x6000, v182
	v_add_u32_e32 v174, 0x6400, v182
	v_mfma_f32_16x16x32_bf16 v[76:79], v[192:195], v[132:135], v[244:247]
	s_and_saveexec_b64 s[0:1], vcc
	s_cbranch_execz .LBB0_215
	ds_write2_b32 v182, v88, v96 offset1:16
	ds_write2_b32 v182, v89, v97 offset0:128 offset1:144
	ds_write2_b32 v183, v90, v98 offset1:16
	ds_write2_b32 v183, v91, v99 offset0:128 offset1:144
	ds_write2_b32 v182, v80, v84 offset0:32 offset1:48
	ds_write2_b32 v182, v81, v85 offset0:160 offset1:176
	ds_write2_b32 v183, v82, v86 offset0:32 offset1:48
	ds_write2_b32 v183, v83, v87 offset0:160 offset1:176
	ds_write2_b32 v182, v120, v124 offset0:64 offset1:80
	ds_write2_b32 v182, v121, v125 offset0:192 offset1:208
	ds_write2_b32 v183, v122, v126 offset0:64 offset1:80
	ds_write2_b32 v183, v123, v127 offset0:192 offset1:208
	ds_write2_b32 v182, v112, v116 offset0:96 offset1:112
	ds_write2_b32 v182, v113, v117 offset0:224 offset1:240
	ds_write2_b32 v183, v114, v118 offset0:96 offset1:112
	ds_write2_b32 v183, v115, v119 offset0:224 offset1:240
	ds_write2_b32 v181, v40, v52 offset1:16
	ds_write2_b32 v181, v41, v53 offset0:128 offset1:144
	ds_write2_b32 v180, v42, v54 offset1:16
	ds_write2_b32 v180, v43, v55 offset0:128 offset1:144
	ds_write2_b32 v181, v32, v36 offset0:32 offset1:48
	ds_write2_b32 v181, v33, v37 offset0:160 offset1:176
	ds_write2_b32 v180, v34, v38 offset0:32 offset1:48
	ds_write2_b32 v180, v35, v39 offset0:160 offset1:176
	ds_write2_b32 v181, v104, v108 offset0:64 offset1:80
	ds_write2_b32 v181, v105, v109 offset0:192 offset1:208
	ds_write2_b32 v180, v106, v110 offset0:64 offset1:80
	ds_write2_b32 v180, v107, v111 offset0:192 offset1:208
	ds_write2_b32 v181, v92, v100 offset0:96 offset1:112
	ds_write2_b32 v181, v93, v101 offset0:224 offset1:240
	ds_write2_b32 v180, v94, v102 offset0:96 offset1:112
	ds_write2_b32 v180, v95, v103 offset0:224 offset1:240
	ds_write2_b32 v179, v24, v28 offset1:16
	ds_write2_b32 v179, v25, v29 offset0:128 offset1:144
	ds_write2_b32 v178, v26, v30 offset1:16
	ds_write2_b32 v178, v27, v31 offset0:128 offset1:144
	ds_write2_b32 v179, v16, v20 offset0:32 offset1:48
	ds_write2_b32 v179, v17, v21 offset0:160 offset1:176
	ds_write2_b32 v178, v18, v22 offset0:32 offset1:48
	ds_write2_b32 v178, v19, v23 offset0:160 offset1:176
	ds_write2_b32 v179, v56, v60 offset0:64 offset1:80
	ds_write2_b32 v179, v57, v61 offset0:192 offset1:208
	ds_write2_b32 v178, v58, v62 offset0:64 offset1:80
	ds_write2_b32 v178, v59, v63 offset0:192 offset1:208
	ds_write2_b32 v179, v44, v72 offset0:96 offset1:112
	ds_write2_b32 v179, v45, v73 offset0:224 offset1:240
	ds_write2_b32 v178, v46, v74 offset0:96 offset1:112
	ds_write2_b32 v178, v47, v75 offset0:224 offset1:240
	ds_write2_b32 v175, v8, v12 offset1:16
	ds_write2_b32 v175, v9, v13 offset0:128 offset1:144
	ds_write2_b32 v174, v10, v14 offset1:16
	ds_write2_b32 v174, v11, v15 offset0:128 offset1:144
	ds_write2_b32 v175, v0, v4 offset0:32 offset1:48
	ds_write2_b32 v175, v1, v5 offset0:160 offset1:176
	ds_write2_b32 v174, v2, v6 offset0:32 offset1:48
	ds_write2_b32 v174, v3, v7 offset0:160 offset1:176
	ds_write2_b32 v175, v48, v64 offset0:64 offset1:80
	ds_write2_b32 v175, v49, v65 offset0:192 offset1:208
	ds_write2_b32 v174, v50, v66 offset0:64 offset1:80
	ds_write2_b32 v174, v51, v67 offset0:192 offset1:208
	ds_write2_b32 v175, v68, v76 offset0:96 offset1:112
	ds_write2_b32 v175, v69, v77 offset0:224 offset1:240
	ds_write2_b32 v174, v70, v78 offset0:96 offset1:112
	ds_write2_b32 v174, v71, v79 offset0:224 offset1:240

.LBB0_659:
	s_add_i32 s1, s0, 0x10000
	s_and_b32 s11, s1, 0x10000
	s_waitcnt vmcnt(0)
	s_barrier
	s_and_b32 s0, s0, 0x10000
	s_add_i32 s0, s0, 0
	v_add_u32_e32 v151, s0, v149
	v_add_u32_e32 v164, v151, v147
	ds_read_b128 v[152:155], v164
	ds_read_b128 v[156:159], v164 offset:2048
	ds_read_b128 v[160:163], v164 offset:4096
	ds_read_b128 v[164:167], v164 offset:6144
	v_add_u32_e32 v251, v151, v146
	v_add_u32_e32 v176, s0, v148
	v_add_u32_e32 v186, v176, v147
	ds_read_b128 v[168:171], v186 offset:32768
	ds_read_b128 v[172:175], v186 offset:34816
	ds_read_b128 v[178:181], v186 offset:36864
	ds_read_b128 v[182:185], v186 offset:38912
	v_add_u32_e32 v250, v176, v146
	ds_read_b128 v[212:215], v186 offset:40960
	ds_read_b128 v[216:219], v186 offset:43008
	ds_read_b128 v[220:223], v186 offset:45056
	ds_read_b128 v[224:227], v186 offset:47104
	v_add_u32_e32 v254, s11, v150
	v_add_u32_e32 v228, 0x2000, v254
	v_readfirstlane_b32 s11, v254
	v_lshl_add_u64 v[188:189], v[128:129], 0, s[2:3]
	s_mov_b32 m0, s11
	v_readfirstlane_b32 s11, v228
	v_add_u32_e32 v228, 0x4000, v254
	global_load_lds_dwordx4 v[188:189], off
	v_lshl_add_u64 v[188:189], v[130:131], 0, s[2:3]
	s_mov_b32 m0, s11
	s_waitcnt lgkmcnt(4)
	v_mfma_f32_16x16x32_bf16 v[124:127], v[152:155], v[168:171], v[124:127]
	ds_read_b128 v[192:195], v251
	v_mfma_f32_16x16x32_bf16 v[120:123], v[152:155], v[172:175], v[120:123]
	ds_read_b128 v[198:201], v251 offset:2048
	v_readfirstlane_b32 s11, v228
	v_add_u32_e32 v228, 0x6000, v254
	v_mfma_f32_16x16x32_bf16 v[116:119], v[152:155], v[178:181], v[116:119]
	ds_read_b128 v[204:207], v251 offset:4096
	global_load_lds_dwordx4 v[188:189], off
	v_lshl_add_u64 v[188:189], v[132:133], 0, s[2:3]
	v_mfma_f32_16x16x32_bf16 v[112:115], v[152:155], v[182:185], v[112:115]
	ds_read_b128 v[208:211], v251 offset:6144
	s_mov_b32 m0, s11
	v_readfirstlane_b32 s11, v228
	v_mfma_f32_16x16x32_bf16 v[104:107], v[156:159], v[168:171], v[104:107]
	global_load_lds_dwordx4 v[188:189], off
	v_lshl_add_u64 v[188:189], v[134:135], 0, s[2:3]
	v_mfma_f32_16x16x32_bf16 v[96:99], v[156:159], v[172:175], v[96:99]
	s_mov_b32 m0, s11
	v_add_u32_e32 v253, 0x8000, v254
	v_mfma_f32_16x16x32_bf16 v[88:91], v[156:159], v[178:181], v[88:91]
	global_load_lds_dwordx4 v[188:189], off
	v_lshl_add_u64 v[188:189], v[136:137], 0, s[2:3]
	v_mfma_f32_16x16x32_bf16 v[80:83], v[156:159], v[182:185], v[80:83]
	s_mov_b64 s[18:19], 0x550080
	v_readfirstlane_b32 s11, v253
	v_mfma_f32_16x16x32_bf16 v[72:75], v[160:163], v[168:171], v[72:75]
	v_add_u32_e32 v253, 0xa000, v254
	v_lshl_add_u64 v[228:229], v[188:189], 0, s[18:19]
	v_mfma_f32_16x16x32_bf16 v[64:67], v[160:163], v[172:175], v[64:67]
	s_mov_b32 m0, s11
	s_mov_b64 s[18:19], 0x572080
	v_mfma_f32_16x16x32_bf16 v[56:59], v[160:163], v[178:181], v[56:59]
	v_readfirstlane_b32 s11, v253
	v_add_u32_e32 v253, 0xc000, v254
	v_mfma_f32_16x16x32_bf16 v[48:51], v[160:163], v[182:185], v[48:51]
	global_load_lds_dwordx4 v[228:229], off
	v_lshl_add_u64 v[228:229], v[188:189], 0, s[18:19]
	v_mfma_f32_16x16x32_bf16 v[40:43], v[164:167], v[168:171], v[40:43]
	s_mov_b32 m0, s11
	s_mov_b64 s[18:19], 0x594080
	v_mfma_f32_16x16x32_bf16 v[32:35], v[164:167], v[172:175], v[32:35]
	v_readfirstlane_b32 s11, v253
	v_add_u32_e32 v254, 0xe000, v254
	v_mfma_f32_16x16x32_bf16 v[24:27], v[164:167], v[178:181], v[24:27]
	global_load_lds_dwordx4 v[228:229], off
	v_lshl_add_u64 v[228:229], v[188:189], 0, s[18:19]
	v_mfma_f32_16x16x32_bf16 v[16:19], v[164:167], v[182:185], v[16:19]
	s_mov_b32 m0, s11
	s_mov_b64 s[18:19], 0x5b6080
	s_waitcnt lgkmcnt(4)
	v_mfma_f32_16x16x32_bf16 v[100:103], v[152:155], v[212:215], v[100:103]
	v_readfirstlane_b32 s11, v254
	global_load_lds_dwordx4 v[228:229], off
	v_mfma_f32_16x16x32_bf16 v[92:95], v[152:155], v[216:219], v[92:95]
	v_lshl_add_u64 v[188:189], v[188:189], 0, s[18:19]
	s_mov_b32 m0, s11
	v_mfma_f32_16x16x32_bf16 v[84:87], v[152:155], v[220:223], v[84:87]
	ds_read_b128 v[168:171], v250 offset:32768
	global_load_lds_dwordx4 v[188:189], off
	v_mfma_f32_16x16x32_bf16 v[76:79], v[152:155], v[224:227], v[76:79]
	ds_read_b128 v[172:175], v250 offset:34816
	v_mfma_f32_16x16x32_bf16 v[68:71], v[156:159], v[212:215], v[68:71]
	ds_read_b128 v[178:181], v250 offset:36864
	v_mfma_f32_16x16x32_bf16 v[60:63], v[156:159], v[216:219], v[60:63]
	ds_read_b128 v[182:185], v250 offset:38912
	v_mfma_f32_16x16x32_bf16 v[52:55], v[156:159], v[220:223], v[52:55]
	v_mfma_f32_16x16x32_bf16 v[44:47], v[156:159], v[224:227], v[44:47]
	v_mfma_f32_16x16x32_bf16 v[36:39], v[160:163], v[212:215], v[36:39]
	v_mfma_f32_16x16x32_bf16 v[28:31], v[160:163], v[216:219], v[28:31]
	v_mfma_f32_16x16x32_bf16 v[20:23], v[160:163], v[220:223], v[20:23]
	v_mfma_f32_16x16x32_bf16 v[12:15], v[160:163], v[224:227], v[12:15]
	v_mfma_f32_16x16x32_bf16 v[8:11], v[164:167], v[212:215], v[8:11]
	v_mfma_f32_16x16x32_bf16 v[4:7], v[164:167], v[216:219], v[4:7]
	v_mfma_f32_16x16x32_bf16 v[0:3], v[164:167], v[220:223], v[0:3]
	v_mfma_f32_16x16x32_bf16 v[108:111], v[164:167], v[224:227], v[108:111]
	s_waitcnt lgkmcnt(0)
	v_mfma_f32_16x16x32_bf16 v[124:127], v[192:195], v[168:171], v[124:127]
	ds_read_b128 v[212:215], v250 offset:40960
	v_mfma_f32_16x16x32_bf16 v[120:123], v[192:195], v[172:175], v[120:123]
	ds_read_b128 v[216:219], v250 offset:43008
	v_mfma_f32_16x16x32_bf16 v[116:119], v[192:195], v[178:181], v[116:119]
	ds_read_b128 v[220:223], v250 offset:45056
	v_mfma_f32_16x16x32_bf16 v[112:115], v[192:195], v[182:185], v[112:115]
	ds_read_b128 v[224:227], v250 offset:47104
	v_mfma_f32_16x16x32_bf16 v[104:107], v[198:201], v[168:171], v[104:107]
	v_mfma_f32_16x16x32_bf16 v[96:99], v[198:201], v[172:175], v[96:99]
	v_mfma_f32_16x16x32_bf16 v[88:91], v[198:201], v[178:181], v[88:91]
	v_mfma_f32_16x16x32_bf16 v[80:83], v[198:201], v[182:185], v[80:83]
	v_mfma_f32_16x16x32_bf16 v[72:75], v[204:207], v[168:171], v[72:75]
	v_mfma_f32_16x16x32_bf16 v[64:67], v[204:207], v[172:175], v[64:67]
	v_mfma_f32_16x16x32_bf16 v[56:59], v[204:207], v[178:181], v[56:59]
	v_mfma_f32_16x16x32_bf16 v[48:51], v[204:207], v[182:185], v[48:51]
	v_mfma_f32_16x16x32_bf16 v[40:43], v[208:211], v[168:171], v[40:43]
	v_mfma_f32_16x16x32_bf16 v[32:35], v[208:211], v[172:175], v[32:35]
	v_mfma_f32_16x16x32_bf16 v[24:27], v[208:211], v[178:181], v[24:27]
	v_mfma_f32_16x16x32_bf16 v[16:19], v[208:211], v[182:185], v[16:19]
	s_waitcnt lgkmcnt(0)
	v_mfma_f32_16x16x32_bf16 v[100:103], v[192:195], v[212:215], v[100:103]
	v_mfma_f32_16x16x32_bf16 v[92:95], v[192:195], v[216:219], v[92:95]
	v_mfma_f32_16x16x32_bf16 v[84:87], v[192:195], v[220:223], v[84:87]
	v_mfma_f32_16x16x32_bf16 v[76:79], v[192:195], v[224:227], v[76:79]
	v_mfma_f32_16x16x32_bf16 v[68:71], v[198:201], v[212:215], v[68:71]
	v_mfma_f32_16x16x32_bf16 v[60:63], v[198:201], v[216:219], v[60:63]
	v_mfma_f32_16x16x32_bf16 v[52:55], v[198:201], v[220:223], v[52:55]
	v_mfma_f32_16x16x32_bf16 v[44:47], v[198:201], v[224:227], v[44:47]
	v_mfma_f32_16x16x32_bf16 v[36:39], v[204:207], v[212:215], v[36:39]
	v_mfma_f32_16x16x32_bf16 v[28:31], v[204:207], v[216:219], v[28:31]
	v_mfma_f32_16x16x32_bf16 v[20:23], v[204:207], v[220:223], v[20:23]
	v_mfma_f32_16x16x32_bf16 v[12:15], v[204:207], v[224:227], v[12:15]
	s_add_u32 s2, s2, 0x80
	s_addc_u32 s3, s3, 0
	s_cmpk_eq_i32 s2, 0x780
	s_mov_b32 s0, s1
	v_mfma_f32_16x16x32_bf16 v[8:11], v[208:211], v[212:215], v[8:11]
	v_mfma_f32_16x16x32_bf16 v[4:7], v[208:211], v[216:219], v[4:7]
	v_mfma_f32_16x16x32_bf16 v[0:3], v[208:211], v[220:223], v[0:3]
	v_mfma_f32_16x16x32_bf16 v[108:111], v[208:211], v[224:227], v[108:111]
	s_cbranch_scc0 .LBB0_659
	s_add_i32 s0, 0, 0x10000
	v_add_u32_e32 v136, s0, v149
	v_add_u32_e32 v137, v136, v147
	s_waitcnt vmcnt(0)
	s_barrier
	ds_read_b128 v[128:131], v137
	ds_read_b128 v[132:135], v137 offset:2048
	ds_read_b128 v[150:153], v137 offset:4096
	ds_read_b128 v[154:157], v137 offset:6144
	v_add_u32_e32 v137, s0, v148
	v_add_u32_e32 v147, v137, v147
	ds_read_b128 v[158:161], v147 offset:32768
	ds_read_b128 v[162:165], v147 offset:34816
	ds_read_b128 v[166:169], v147 offset:36864
	ds_read_b128 v[170:173], v147 offset:38912
	s_waitcnt lgkmcnt(0)
	v_mfma_f32_16x16x32_bf16 v[124:127], v[128:131], v[158:161], v[124:127]
	v_mfma_f32_16x16x32_bf16 v[120:123], v[128:131], v[162:165], v[120:123]
	v_mfma_f32_16x16x32_bf16 v[116:119], v[128:131], v[166:169], v[116:119]
	v_mfma_f32_16x16x32_bf16 v[112:115], v[128:131], v[170:173], v[112:115]
	v_mfma_f32_16x16x32_bf16 v[104:107], v[132:135], v[158:161], v[104:107]
	v_mfma_f32_16x16x32_bf16 v[72:75], v[150:153], v[158:161], v[72:75]
	v_mfma_f32_16x16x32_bf16 v[64:67], v[150:153], v[162:165], v[64:67]
	v_mfma_f32_16x16x32_bf16 v[56:59], v[150:153], v[166:169], v[56:59]
	v_mfma_f32_16x16x32_bf16 v[48:51], v[150:153], v[170:173], v[48:51]
	v_mfma_f32_16x16x32_bf16 v[178:181], v[132:135], v[162:165], v[96:99]
	v_mfma_f32_16x16x32_bf16 v[182:185], v[132:135], v[166:169], v[88:91]
	v_mfma_f32_16x16x32_bf16 v[186:189], v[132:135], v[170:173], v[80:83]
	v_mfma_f32_16x16x32_bf16 v[158:161], v[154:157], v[158:161], v[40:43]
	v_mfma_f32_16x16x32_bf16 v[162:165], v[154:157], v[162:165], v[32:35]
	v_mfma_f32_16x16x32_bf16 v[166:169], v[154:157], v[166:169], v[24:27]
	v_mfma_f32_16x16x32_bf16 v[170:173], v[154:157], v[170:173], v[16:19]
	s_nop 2
	ds_read_b128 v[16:19], v147 offset:40960
	ds_read_b128 v[24:27], v147 offset:43008
	ds_read_b128 v[32:35], v147 offset:45056
	ds_read_b128 v[40:43], v147 offset:47104
	s_waitcnt lgkmcnt(0)
	v_mfma_f32_16x16x32_bf16 v[100:103], v[128:131], v[16:19], v[100:103]
	v_mfma_f32_16x16x32_bf16 v[92:95], v[128:131], v[24:27], v[92:95]
	v_mfma_f32_16x16x32_bf16 v[192:195], v[128:131], v[32:35], v[84:87]
	v_mfma_f32_16x16x32_bf16 v[76:79], v[128:131], v[40:43], v[76:79]
	v_mfma_f32_16x16x32_bf16 v[68:71], v[132:135], v[16:19], v[68:71]
	v_mfma_f32_16x16x32_bf16 v[60:63], v[132:135], v[24:27], v[60:63]
	v_mfma_f32_16x16x32_bf16 v[128:131], v[132:135], v[32:35], v[52:55]
	v_mfma_f32_16x16x32_bf16 v[44:47], v[132:135], v[40:43], v[44:47]
	v_mfma_f32_16x16x32_bf16 v[132:135], v[150:153], v[16:19], v[36:39]
	v_mfma_f32_16x16x32_bf16 v[198:201], v[150:153], v[24:27], v[28:31]
	v_mfma_f32_16x16x32_bf16 v[204:207], v[150:153], v[32:35], v[20:23]
	v_mfma_f32_16x16x32_bf16 v[148:151], v[150:153], v[40:43], v[12:15]
	v_mfma_f32_16x16x32_bf16 v[208:211], v[154:157], v[16:19], v[8:11]
	v_mfma_f32_16x16x32_bf16 v[212:215], v[154:157], v[24:27], v[4:7]
	v_mfma_f32_16x16x32_bf16 v[216:219], v[154:157], v[32:35], v[0:3]
	v_mfma_f32_16x16x32_bf16 v[154:157], v[154:157], v[40:43], v[108:111]
	s_nop 1
	v_add_u32_e32 v0, v136, v146
	v_add_u32_e32 v136, v137, v146
	ds_read_b128 v[108:111], v0
	ds_read_b128 v[220:223], v0 offset:2048
	ds_read_b128 v[224:227], v0 offset:4096
	ds_read_b128 v[228:231], v0 offset:6144
	ds_read_b128 v[0:3], v136 offset:32768
	ds_read_b128 v[4:7], v136 offset:34816
	ds_read_b128 v[232:235], v136 offset:36864
	ds_read_b128 v[236:239], v136 offset:38912
	s_waitcnt lgkmcnt(0)
	v_mfma_f32_16x16x32_bf16 v[88:91], v[108:111], v[0:3], v[124:127]
	v_mfma_f32_16x16x32_bf16 v[96:99], v[108:111], v[4:7], v[120:123]
	v_mfma_f32_16x16x32_bf16 v[80:83], v[108:111], v[232:235], v[116:119]
	v_mfma_f32_16x16x32_bf16 v[84:87], v[108:111], v[236:239], v[112:115]
	v_mfma_f32_16x16x32_bf16 v[40:43], v[220:223], v[0:3], v[104:107]
	v_mfma_f32_16x16x32_bf16 v[52:55], v[220:223], v[4:7], v[178:181]
	v_mfma_f32_16x16x32_bf16 v[32:35], v[220:223], v[232:235], v[182:185]
	v_mfma_f32_16x16x32_bf16 v[36:39], v[220:223], v[236:239], v[186:189]
	v_mfma_f32_16x16x32_bf16 v[24:27], v[224:227], v[0:3], v[72:75]
	v_mfma_f32_16x16x32_bf16 v[28:31], v[224:227], v[4:7], v[64:67]
	v_mfma_f32_16x16x32_bf16 v[16:19], v[224:227], v[232:235], v[56:59]
	v_mfma_f32_16x16x32_bf16 v[20:23], v[224:227], v[236:239], v[48:51]
	v_mfma_f32_16x16x32_bf16 v[8:11], v[228:231], v[0:3], v[158:161]
	v_mfma_f32_16x16x32_bf16 v[12:15], v[228:231], v[4:7], v[162:165]
	v_mfma_f32_16x16x32_bf16 v[0:3], v[228:231], v[232:235], v[166:169]
	v_mfma_f32_16x16x32_bf16 v[4:7], v[228:231], v[236:239], v[170:173]
	ds_read_b128 v[48:51], v136 offset:40960
	ds_read_b128 v[64:67], v136 offset:43008
	ds_read_b128 v[158:161], v136 offset:45056
	ds_read_b128 v[162:165], v136 offset:47104
	s_waitcnt lgkmcnt(0)
	v_mfma_f32_16x16x32_bf16 v[104:107], v[220:223], v[48:51], v[68:71]
	v_cmp_ne_u32_e32 vcc, 0, v138
	v_cmp_eq_u32_e64 s[2:3], 0, v138
	s_waitcnt vmcnt(0)
	v_lshl_or_b32 v68, v140, 2, v141
	v_lshl_add_u32 v69, v139, 2, 0
	v_mfma_f32_16x16x32_bf16 v[120:123], v[108:111], v[48:51], v[100:103]
	v_lshl_add_u32 v152, v68, 9, v69
	v_add_u32_e32 v153, 0x400, v152
	v_add_u32_e32 v147, 0x6000, v152
	v_mfma_f32_16x16x32_bf16 v[124:127], v[108:111], v[64:67], v[92:95]
	v_add_u32_e32 v146, 0x6400, v152
	s_barrier
	v_mfma_f32_16x16x32_bf16 v[112:115], v[108:111], v[158:161], v[192:195]
	v_mfma_f32_16x16x32_bf16 v[116:119], v[108:111], v[162:165], v[76:79]
	v_mfma_f32_16x16x32_bf16 v[108:111], v[220:223], v[64:67], v[60:63]
	v_mfma_f32_16x16x32_bf16 v[92:95], v[220:223], v[158:161], v[128:131]
	v_mfma_f32_16x16x32_bf16 v[100:103], v[220:223], v[162:165], v[44:47]
	v_mfma_f32_16x16x32_bf16 v[56:59], v[224:227], v[48:51], v[132:135]
	v_mfma_f32_16x16x32_bf16 v[60:63], v[224:227], v[64:67], v[198:201]
	v_mfma_f32_16x16x32_bf16 v[44:47], v[224:227], v[158:161], v[204:207]
	v_mfma_f32_16x16x32_bf16 v[72:75], v[224:227], v[162:165], v[148:151]
	v_mfma_f32_16x16x32_bf16 v[48:51], v[228:231], v[48:51], v[208:211]
	s_nop 1
	v_add_u32_e32 v151, 0x2000, v152
	v_add_u32_e32 v150, 0x2400, v152
	v_add_u32_e32 v149, 0x4000, v152
	v_mfma_f32_16x16x32_bf16 v[64:67], v[228:231], v[64:67], v[212:215]
	v_add_u32_e32 v148, 0x4400, v152
	v_mfma_f32_16x16x32_bf16 v[68:71], v[228:231], v[158:161], v[216:219]
	v_mfma_f32_16x16x32_bf16 v[76:79], v[228:231], v[162:165], v[154:157]
	s_and_saveexec_b64 s[0:1], s[2:3]
	s_cbranch_execz .LBB0_662
	ds_write2_b32 v152, v88, v96 offset1:16
	ds_write2_b32 v152, v89, v97 offset0:128 offset1:144
	ds_write2_b32 v153, v90, v98 offset1:16
	ds_write2_b32 v153, v91, v99 offset0:128 offset1:144
	ds_write2_b32 v152, v80, v84 offset0:32 offset1:48
	ds_write2_b32 v152, v81, v85 offset0:160 offset1:176
	ds_write2_b32 v153, v82, v86 offset0:32 offset1:48
	ds_write2_b32 v153, v83, v87 offset0:160 offset1:176
	ds_write2_b32 v152, v120, v124 offset0:64 offset1:80
	ds_write2_b32 v152, v121, v125 offset0:192 offset1:208
	ds_write2_b32 v153, v122, v126 offset0:64 offset1:80
	ds_write2_b32 v153, v123, v127 offset0:192 offset1:208
	ds_write2_b32 v152, v112, v116 offset0:96 offset1:112
	ds_write2_b32 v152, v113, v117 offset0:224 offset1:240
	ds_write2_b32 v153, v114, v118 offset0:96 offset1:112
	ds_write2_b32 v153, v115, v119 offset0:224 offset1:240
	ds_write2_b32 v151, v40, v52 offset1:16
	ds_write2_b32 v151, v41, v53 offset0:128 offset1:144
	ds_write2_b32 v150, v42, v54 offset1:16
	ds_write2_b32 v150, v43, v55 offset0:128 offset1:144
	ds_write2_b32 v151, v32, v36 offset0:32 offset1:48
	ds_write2_b32 v151, v33, v37 offset0:160 offset1:176
	ds_write2_b32 v150, v34, v38 offset0:32 offset1:48
	ds_write2_b32 v150, v35, v39 offset0:160 offset1:176
	ds_write2_b32 v151, v104, v108 offset0:64 offset1:80
	ds_write2_b32 v151, v105, v109 offset0:192 offset1:208
	ds_write2_b32 v150, v106, v110 offset0:64 offset1:80
	ds_write2_b32 v150, v107, v111 offset0:192 offset1:208
	ds_write2_b32 v151, v92, v100 offset0:96 offset1:112
	ds_write2_b32 v151, v93, v101 offset0:224 offset1:240
	ds_write2_b32 v150, v94, v102 offset0:96 offset1:112
	ds_write2_b32 v150, v95, v103 offset0:224 offset1:240
	ds_write2_b32 v149, v24, v28 offset1:16
	ds_write2_b32 v149, v25, v29 offset0:128 offset1:144
	ds_write2_b32 v148, v26, v30 offset1:16
	ds_write2_b32 v148, v27, v31 offset0:128 offset1:144
	ds_write2_b32 v149, v16, v20 offset0:32 offset1:48
	ds_write2_b32 v149, v17, v21 offset0:160 offset1:176
	ds_write2_b32 v148, v18, v22 offset0:32 offset1:48
	ds_write2_b32 v148, v19, v23 offset0:160 offset1:176
	ds_write2_b32 v149, v56, v60 offset0:64 offset1:80
	ds_write2_b32 v149, v57, v61 offset0:192 offset1:208
	ds_write2_b32 v148, v58, v62 offset0:64 offset1:80
	ds_write2_b32 v148, v59, v63 offset0:192 offset1:208
	ds_write2_b32 v149, v44, v72 offset0:96 offset1:112
	ds_write2_b32 v149, v45, v73 offset0:224 offset1:240
	ds_write2_b32 v148, v46, v74 offset0:96 offset1:112
	ds_write2_b32 v148, v47, v75 offset0:224 offset1:240
	ds_write2_b32 v147, v8, v12 offset1:16
	ds_write2_b32 v147, v9, v13 offset0:128 offset1:144
	ds_write2_b32 v146, v10, v14 offset1:16
	ds_write2_b32 v146, v11, v15 offset0:128 offset1:144
	ds_write2_b32 v147, v0, v4 offset0:32 offset1:48
	ds_write2_b32 v147, v1, v5 offset0:160 offset1:176
	ds_write2_b32 v146, v2, v6 offset0:32 offset1:48
	ds_write2_b32 v146, v3, v7 offset0:160 offset1:176
	ds_write2_b32 v147, v48, v64 offset0:64 offset1:80
	ds_write2_b32 v147, v49, v65 offset0:192 offset1:208
	ds_write2_b32 v146, v50, v66 offset0:64 offset1:80
	ds_write2_b32 v146, v51, v67 offset0:192 offset1:208
	ds_write2_b32 v147, v68, v76 offset0:96 offset1:112
	ds_write2_b32 v147, v69, v77 offset0:224 offset1:240
	ds_write2_b32 v146, v70, v78 offset0:96 offset1:112
	ds_write2_b32 v146, v71, v79 offset0:224 offset1:240
.LBB0_662:
	s_or_b64 exec, exec, s[0:1]
	s_mul_hi_i32 s0, s10, 0x3e0f83e1
	s_lshr_b32 s1, s0, 31
	s_ashr_i32 s0, s0, 3
	s_add_i32 s0, s0, s1
	s_mul_hi_i32 s1, s0, 0x6000
	s_mulk_i32 s0, 0x6000
	s_add_u32 s0, s14, s0
	s_addc_u32 s1, s15, s1
	s_add_u32 s10, s0, 0x2000
	v_or_b32_e32 v136, s12, v143
	s_addc_u32 s11, s1, 0
	v_lshlrev_b32_e32 v132, 2, v136
	s_waitcnt lgkmcnt(0)
	s_barrier
	global_load_dwordx4 v[128:131], v132, s[10:11] offset:16
	s_nop 0
	global_load_dwordx4 v[132:135], v132, s[10:11]
	v_add_u32_e32 v137, s13, v144
	s_load_dwordx2 s[24:25], s[40:41], 0xe8
	v_lshlrev_b32_e32 v176, 2, v136
	v_lshrrev_b32_e32 v249, 13, v137
	v_min_u32_e32 v249, 1, v249
	v_lshlrev_b32_e32 v249, 8, v249
	v_sub_u32_e32 v249, v137, v249
	v_lshlrev_b32_e32 v249, 12, v249
	v_lshl_add_u32 v249, v136, 2, v249
	v_add_u32_e32 v248, 0x10000, v145
	s_waitcnt lgkmcnt(0)
	s_add_u32 s26, s24, 0x80000
	s_addc_u32 s27, s25, 0
	v_mov_b32_e32 v254, v249
	v_add_u32_e32 v253, 0x20000, v249
	v_add_u32_e32 v251, 0x40000, v249
	v_add_u32_e32 v250, 0x60000, v249
	global_load_dwordx4 v[138:141], v254, s[24:25]
	global_load_dwordx4 v[154:157], v254, s[24:25] offset:16
	global_load_dwordx4 v[158:161], v253, s[24:25]
	global_load_dwordx4 v[162:165], v253, s[24:25] offset:16
	global_load_dwordx4 v[166:169], v251, s[24:25]
	global_load_dwordx4 v[170:173], v251, s[24:25] offset:16
	global_load_dwordx4 v[178:181], v250, s[24:25]
	global_load_dwordx4 v[182:185], v250, s[24:25] offset:16
	global_load_dwordx4 v[186:189], v254, s[26:27]
	global_load_dwordx4 v[192:195], v254, s[26:27] offset:16
	global_load_dwordx4 v[198:201], v253, s[26:27]
	global_load_dwordx4 v[204:207], v253, s[26:27] offset:16
	global_load_dwordx4 v[208:211], v251, s[26:27]
	global_load_dwordx4 v[212:215], v251, s[26:27] offset:16
	global_load_dwordx4 v[216:219], v250, s[26:27]
	global_load_dwordx4 v[220:223], v250, s[26:27] offset:16
	ds_read_b128 v[224:227], v145
	ds_read_b128 v[228:231], v145 offset:16
	ds_read_b128 v[232:235], v145 offset:16384
	ds_read_b128 v[236:239], v145 offset:16400
	s_waitcnt vmcnt(14)
	v_pk_mul_f32 v[140:141], v[140:141], s[34:35] op_sel_hi:[1,0]
	v_pk_mul_f32 v[138:139], v[138:139], s[34:35] op_sel_hi:[1,0]
	v_pk_mul_f32 v[156:157], v[156:157], s[34:35] op_sel_hi:[1,0]
	v_pk_mul_f32 v[154:155], v[154:155], s[34:35] op_sel_hi:[1,0]
	s_waitcnt lgkmcnt(2)
	v_pk_fma_f32 v[140:141], v[134:135], v[226:227], v[140:141]
	v_pk_fma_f32 v[138:139], v[132:133], v[224:225], v[138:139]
	v_pk_fma_f32 v[156:157], v[130:131], v[230:231], v[156:157]
	v_pk_fma_f32 v[154:155], v[128:129], v[228:229], v[154:155]
	ds_read_b128 v[224:227], v145 offset:32768
	ds_read_b128 v[228:231], v145 offset:32784
	global_store_dwordx4 v254, v[138:141], s[24:25]
	global_store_dwordx4 v254, v[154:157], s[24:25] offset:16
	s_waitcnt vmcnt(14)
	v_pk_mul_f32 v[160:161], v[160:161], s[34:35] op_sel_hi:[1,0]
	v_pk_mul_f32 v[158:159], v[158:159], s[34:35] op_sel_hi:[1,0]
	v_pk_mul_f32 v[164:165], v[164:165], s[34:35] op_sel_hi:[1,0]
	v_pk_mul_f32 v[162:163], v[162:163], s[34:35] op_sel_hi:[1,0]
	s_waitcnt lgkmcnt(2)
	v_pk_fma_f32 v[160:161], v[134:135], v[234:235], v[160:161]
	v_pk_fma_f32 v[158:159], v[132:133], v[232:233], v[158:159]
	v_pk_fma_f32 v[164:165], v[130:131], v[238:239], v[164:165]
	v_pk_fma_f32 v[162:163], v[128:129], v[236:237], v[162:163]
	ds_read_b128 v[232:235], v145 offset:49152
	ds_read_b128 v[236:239], v145 offset:49168
	global_store_dwordx4 v253, v[158:161], s[24:25]
	global_store_dwordx4 v253, v[162:165], s[24:25] offset:16
	s_waitcnt vmcnt(14)
	v_pk_mul_f32 v[168:169], v[168:169], s[34:35] op_sel_hi:[1,0]
	v_pk_mul_f32 v[166:167], v[166:167], s[34:35] op_sel_hi:[1,0]
	v_pk_mul_f32 v[172:173], v[172:173], s[34:35] op_sel_hi:[1,0]
	v_pk_mul_f32 v[170:171], v[170:171], s[34:35] op_sel_hi:[1,0]
	s_waitcnt lgkmcnt(2)
	v_pk_fma_f32 v[168:169], v[134:135], v[226:227], v[168:169]
	v_pk_fma_f32 v[166:167], v[132:133], v[224:225], v[166:167]
	v_pk_fma_f32 v[172:173], v[130:131], v[230:231], v[172:173]
	v_pk_fma_f32 v[170:171], v[128:129], v[228:229], v[170:171]
	ds_read_b128 v[224:227], v248
	ds_read_b128 v[228:231], v248 offset:16
	global_store_dwordx4 v251, v[166:169], s[24:25]
	global_store_dwordx4 v251, v[170:173], s[24:25] offset:16
	s_waitcnt vmcnt(14)
	v_pk_mul_f32 v[180:181], v[180:181], s[34:35] op_sel_hi:[1,0]
	v_pk_mul_f32 v[178:179], v[178:179], s[34:35] op_sel_hi:[1,0]
	v_pk_mul_f32 v[184:185], v[184:185], s[34:35] op_sel_hi:[1,0]
	v_pk_mul_f32 v[182:183], v[182:183], s[34:35] op_sel_hi:[1,0]
	s_waitcnt lgkmcnt(2)
	v_pk_fma_f32 v[180:181], v[134:135], v[234:235], v[180:181]
	v_pk_fma_f32 v[178:179], v[132:133], v[232:233], v[178:179]
	v_pk_fma_f32 v[184:185], v[130:131], v[238:239], v[184:185]
	v_pk_fma_f32 v[182:183], v[128:129], v[236:237], v[182:183]
	ds_read_b128 v[232:235], v248 offset:16384
	ds_read_b128 v[236:239], v248 offset:16400
	global_store_dwordx4 v250, v[178:181], s[24:25]
	global_store_dwordx4 v250, v[182:185], s[24:25] offset:16
	s_waitcnt vmcnt(14)
	v_pk_mul_f32 v[188:189], v[188:189], s[34:35] op_sel_hi:[1,0]
	v_pk_mul_f32 v[186:187], v[186:187], s[34:35] op_sel_hi:[1,0]
	v_pk_mul_f32 v[194:195], v[194:195], s[34:35] op_sel_hi:[1,0]
	v_pk_mul_f32 v[192:193], v[192:193], s[34:35] op_sel_hi:[1,0]
	s_waitcnt lgkmcnt(2)
	v_pk_fma_f32 v[188:189], v[134:135], v[226:227], v[188:189]
	v_pk_fma_f32 v[186:187], v[132:133], v[224:225], v[186:187]
	v_pk_fma_f32 v[194:195], v[130:131], v[230:231], v[194:195]
	v_pk_fma_f32 v[192:193], v[128:129], v[228:229], v[192:193]
	ds_read_b128 v[224:227], v248 offset:32768
	ds_read_b128 v[228:231], v248 offset:32784
	global_store_dwordx4 v254, v[186:189], s[26:27]
	global_store_dwordx4 v254, v[192:195], s[26:27] offset:16
	s_waitcnt vmcnt(14)
	v_pk_mul_f32 v[200:201], v[200:201], s[34:35] op_sel_hi:[1,0]
	v_pk_mul_f32 v[198:199], v[198:199], s[34:35] op_sel_hi:[1,0]
	v_pk_mul_f32 v[206:207], v[206:207], s[34:35] op_sel_hi:[1,0]
	v_pk_mul_f32 v[204:205], v[204:205], s[34:35] op_sel_hi:[1,0]
	s_waitcnt lgkmcnt(2)
	v_pk_fma_f32 v[200:201], v[134:135], v[234:235], v[200:201]
	v_pk_fma_f32 v[198:199], v[132:133], v[232:233], v[198:199]
	v_pk_fma_f32 v[206:207], v[130:131], v[238:239], v[206:207]
	v_pk_fma_f32 v[204:205], v[128:129], v[236:237], v[204:205]
	ds_read_b128 v[232:235], v248 offset:49152
	ds_read_b128 v[236:239], v248 offset:49168
	global_store_dwordx4 v253, v[198:201], s[26:27]
	global_store_dwordx4 v253, v[204:207], s[26:27] offset:16
	s_waitcnt vmcnt(14)
	v_pk_mul_f32 v[210:211], v[210:211], s[34:35] op_sel_hi:[1,0]
	v_pk_mul_f32 v[208:209], v[208:209], s[34:35] op_sel_hi:[1,0]
	v_pk_mul_f32 v[214:215], v[214:215], s[34:35] op_sel_hi:[1,0]
	v_pk_mul_f32 v[212:213], v[212:213], s[34:35] op_sel_hi:[1,0]
	s_waitcnt lgkmcnt(2)
	v_pk_fma_f32 v[210:211], v[134:135], v[226:227], v[210:211]
	v_pk_fma_f32 v[208:209], v[132:133], v[224:225], v[208:209]
	v_pk_fma_f32 v[214:215], v[130:131], v[230:231], v[214:215]
	v_pk_fma_f32 v[212:213], v[128:129], v[228:229], v[212:213]
	global_store_dwordx4 v251, v[208:211], s[26:27]
	global_store_dwordx4 v251, v[212:215], s[26:27] offset:16
	s_waitcnt vmcnt(14)
	v_pk_mul_f32 v[218:219], v[218:219], s[34:35] op_sel_hi:[1,0]
	v_pk_mul_f32 v[216:217], v[216:217], s[34:35] op_sel_hi:[1,0]
	v_pk_mul_f32 v[222:223], v[222:223], s[34:35] op_sel_hi:[1,0]
	v_pk_mul_f32 v[220:221], v[220:221], s[34:35] op_sel_hi:[1,0]
	s_waitcnt lgkmcnt(0)
	v_pk_fma_f32 v[218:219], v[134:135], v[234:235], v[218:219]
	v_pk_fma_f32 v[216:217], v[132:133], v[232:233], v[216:217]
	v_pk_fma_f32 v[222:223], v[130:131], v[238:239], v[222:223]
	v_pk_fma_f32 v[220:221], v[128:129], v[236:237], v[220:221]
	global_store_dwordx4 v250, v[216:219], s[26:27]
	global_store_dwordx4 v250, v[220:223], s[26:27] offset:16

.LBB0_674:
	s_or_b64 exec, exec, s[0:1]
	v_lshl_or_b32 v4, v136, 2, v191
	s_waitcnt lgkmcnt(0)
	s_barrier
	global_load_dwordx4 v[0:3], v4, s[10:11] offset:16
	s_nop 0
	global_load_dwordx4 v[4:7], v4, s[10:11]
	s_load_dwordx2 s[24:25], s[40:41], 0xe8
	v_lshlrev_b32_e32 v176, 2, v136
	v_lshrrev_b32_e32 v249, 13, v137
	v_min_u32_e32 v249, 1, v249
	v_lshlrev_b32_e32 v249, 8, v249
	v_sub_u32_e32 v249, v137, v249
	v_lshlrev_b32_e32 v249, 12, v249
	v_lshl_add_u32 v249, v136, 2, v249
	v_add_u32_e32 v248, 0x10000, v145
	s_waitcnt lgkmcnt(0)
	s_add_u32 s26, s24, 0x80000
	s_addc_u32 s27, s25, 0
	v_mov_b32_e32 v254, v249
	v_add_u32_e32 v253, 0x20000, v249
	v_add_u32_e32 v251, 0x40000, v249
	v_add_u32_e32 v250, 0x60000, v249
	global_load_dwordx4 v[8:11], v254, s[24:25] offset:512
	global_load_dwordx4 v[12:15], v254, s[24:25] offset:528
	global_load_dwordx4 v[16:19], v253, s[24:25] offset:512
	global_load_dwordx4 v[20:23], v253, s[24:25] offset:528
	global_load_dwordx4 v[24:27], v251, s[24:25] offset:512
	global_load_dwordx4 v[170:173], v251, s[24:25] offset:528
	global_load_dwordx4 v[178:181], v250, s[24:25] offset:512
	global_load_dwordx4 v[182:185], v250, s[24:25] offset:528
	global_load_dwordx4 v[186:189], v254, s[26:27] offset:512
	global_load_dwordx4 v[192:195], v254, s[26:27] offset:528
	global_load_dwordx4 v[198:201], v253, s[26:27] offset:512
	global_load_dwordx4 v[204:207], v253, s[26:27] offset:528
	global_load_dwordx4 v[208:211], v251, s[26:27] offset:512
	global_load_dwordx4 v[212:215], v251, s[26:27] offset:528
	global_load_dwordx4 v[216:219], v250, s[26:27] offset:512
	global_load_dwordx4 v[220:223], v250, s[26:27] offset:528
	ds_read_b128 v[224:227], v145
	ds_read_b128 v[228:231], v145 offset:16
	ds_read_b128 v[232:235], v145 offset:16384
	ds_read_b128 v[236:239], v145 offset:16400
	s_waitcnt vmcnt(14)
	v_pk_mul_f32 v[10:11], v[10:11], s[34:35] op_sel_hi:[1,0]
	v_pk_mul_f32 v[8:9], v[8:9], s[34:35] op_sel_hi:[1,0]
	v_pk_mul_f32 v[14:15], v[14:15], s[34:35] op_sel_hi:[1,0]
	v_pk_mul_f32 v[12:13], v[12:13], s[34:35] op_sel_hi:[1,0]
	s_waitcnt lgkmcnt(2)
	v_pk_fma_f32 v[10:11], v[6:7], v[226:227], v[10:11]
	v_pk_fma_f32 v[8:9], v[4:5], v[224:225], v[8:9]
	v_pk_fma_f32 v[14:15], v[2:3], v[230:231], v[14:15]
	v_pk_fma_f32 v[12:13], v[0:1], v[228:229], v[12:13]
	ds_read_b128 v[224:227], v145 offset:32768
	ds_read_b128 v[228:231], v145 offset:32784
	global_store_dwordx4 v254, v[8:11], s[24:25] offset:512
	global_store_dwordx4 v254, v[12:15], s[24:25] offset:528
	s_waitcnt vmcnt(14)
	v_pk_mul_f32 v[18:19], v[18:19], s[34:35] op_sel_hi:[1,0]
	v_pk_mul_f32 v[16:17], v[16:17], s[34:35] op_sel_hi:[1,0]
	v_pk_mul_f32 v[22:23], v[22:23], s[34:35] op_sel_hi:[1,0]
	v_pk_mul_f32 v[20:21], v[20:21], s[34:35] op_sel_hi:[1,0]
	s_waitcnt lgkmcnt(2)
	v_pk_fma_f32 v[18:19], v[6:7], v[234:235], v[18:19]
	v_pk_fma_f32 v[16:17], v[4:5], v[232:233], v[16:17]
	v_pk_fma_f32 v[22:23], v[2:3], v[238:239], v[22:23]
	v_pk_fma_f32 v[20:21], v[0:1], v[236:237], v[20:21]
	ds_read_b128 v[232:235], v145 offset:49152
	ds_read_b128 v[236:239], v145 offset:49168
	global_store_dwordx4 v253, v[16:19], s[24:25] offset:512
	global_store_dwordx4 v253, v[20:23], s[24:25] offset:528
	s_waitcnt vmcnt(14)
	v_pk_mul_f32 v[26:27], v[26:27], s[34:35] op_sel_hi:[1,0]
	v_pk_mul_f32 v[24:25], v[24:25], s[34:35] op_sel_hi:[1,0]
	v_pk_mul_f32 v[172:173], v[172:173], s[34:35] op_sel_hi:[1,0]
	v_pk_mul_f32 v[170:171], v[170:171], s[34:35] op_sel_hi:[1,0]
	s_waitcnt lgkmcnt(2)
	v_pk_fma_f32 v[26:27], v[6:7], v[226:227], v[26:27]
	v_pk_fma_f32 v[24:25], v[4:5], v[224:225], v[24:25]
	v_pk_fma_f32 v[172:173], v[2:3], v[230:231], v[172:173]
	v_pk_fma_f32 v[170:171], v[0:1], v[228:229], v[170:171]
	ds_read_b128 v[224:227], v248
	ds_read_b128 v[228:231], v248 offset:16
	global_store_dwordx4 v251, v[24:27], s[24:25] offset:512
	global_store_dwordx4 v251, v[170:173], s[24:25] offset:528
	s_waitcnt vmcnt(14)
	v_pk_mul_f32 v[180:181], v[180:181], s[34:35] op_sel_hi:[1,0]
	v_pk_mul_f32 v[178:179], v[178:179], s[34:35] op_sel_hi:[1,0]
	v_pk_mul_f32 v[184:185], v[184:185], s[34:35] op_sel_hi:[1,0]
	v_pk_mul_f32 v[182:183], v[182:183], s[34:35] op_sel_hi:[1,0]
	s_waitcnt lgkmcnt(2)
	v_pk_fma_f32 v[180:181], v[6:7], v[234:235], v[180:181]
	v_pk_fma_f32 v[178:179], v[4:5], v[232:233], v[178:179]
	v_pk_fma_f32 v[184:185], v[2:3], v[238:239], v[184:185]
	v_pk_fma_f32 v[182:183], v[0:1], v[236:237], v[182:183]
	ds_read_b128 v[232:235], v248 offset:16384
	ds_read_b128 v[236:239], v248 offset:16400
	global_store_dwordx4 v250, v[178:181], s[24:25] offset:512
	global_store_dwordx4 v250, v[182:185], s[24:25] offset:528
	s_waitcnt vmcnt(14)
	v_pk_mul_f32 v[188:189], v[188:189], s[34:35] op_sel_hi:[1,0]
	v_pk_mul_f32 v[186:187], v[186:187], s[34:35] op_sel_hi:[1,0]
	v_pk_mul_f32 v[194:195], v[194:195], s[34:35] op_sel_hi:[1,0]
	v_pk_mul_f32 v[192:193], v[192:193], s[34:35] op_sel_hi:[1,0]
	s_waitcnt lgkmcnt(2)
	v_pk_fma_f32 v[188:189], v[6:7], v[226:227], v[188:189]
	v_pk_fma_f32 v[186:187], v[4:5], v[224:225], v[186:187]
	v_pk_fma_f32 v[194:195], v[2:3], v[230:231], v[194:195]
	v_pk_fma_f32 v[192:193], v[0:1], v[228:229], v[192:193]
	ds_read_b128 v[224:227], v248 offset:32768
	ds_read_b128 v[228:231], v248 offset:32784
	global_store_dwordx4 v254, v[186:189], s[26:27] offset:512
	global_store_dwordx4 v254, v[192:195], s[26:27] offset:528
	s_waitcnt vmcnt(14)
	v_pk_mul_f32 v[200:201], v[200:201], s[34:35] op_sel_hi:[1,0]
	v_pk_mul_f32 v[198:199], v[198:199], s[34:35] op_sel_hi:[1,0]
	v_pk_mul_f32 v[206:207], v[206:207], s[34:35] op_sel_hi:[1,0]
	v_pk_mul_f32 v[204:205], v[204:205], s[34:35] op_sel_hi:[1,0]
	s_waitcnt lgkmcnt(2)
	v_pk_fma_f32 v[200:201], v[6:7], v[234:235], v[200:201]
	v_pk_fma_f32 v[198:199], v[4:5], v[232:233], v[198:199]
	v_pk_fma_f32 v[206:207], v[2:3], v[238:239], v[206:207]
	v_pk_fma_f32 v[204:205], v[0:1], v[236:237], v[204:205]
	ds_read_b128 v[232:235], v248 offset:49152
	ds_read_b128 v[236:239], v248 offset:49168
	global_store_dwordx4 v253, v[198:201], s[26:27] offset:512
	global_store_dwordx4 v253, v[204:207], s[26:27] offset:528
	s_waitcnt vmcnt(14)
	v_pk_mul_f32 v[210:211], v[210:211], s[34:35] op_sel_hi:[1,0]
	v_pk_mul_f32 v[208:209], v[208:209], s[34:35] op_sel_hi:[1,0]
	v_pk_mul_f32 v[214:215], v[214:215], s[34:35] op_sel_hi:[1,0]
	v_pk_mul_f32 v[212:213], v[212:213], s[34:35] op_sel_hi:[1,0]
	s_waitcnt lgkmcnt(2)
	v_pk_fma_f32 v[210:211], v[6:7], v[226:227], v[210:211]
	v_pk_fma_f32 v[208:209], v[4:5], v[224:225], v[208:209]
	v_pk_fma_f32 v[214:215], v[2:3], v[230:231], v[214:215]
	v_pk_fma_f32 v[212:213], v[0:1], v[228:229], v[212:213]
	global_store_dwordx4 v251, v[208:211], s[26:27] offset:512
	global_store_dwordx4 v251, v[212:215], s[26:27] offset:528
	s_waitcnt vmcnt(14)
	v_pk_mul_f32 v[218:219], v[218:219], s[34:35] op_sel_hi:[1,0]
	v_pk_mul_f32 v[216:217], v[216:217], s[34:35] op_sel_hi:[1,0]
	v_pk_mul_f32 v[222:223], v[222:223], s[34:35] op_sel_hi:[1,0]
	v_pk_mul_f32 v[220:221], v[220:221], s[34:35] op_sel_hi:[1,0]
	s_waitcnt lgkmcnt(0)
	v_pk_fma_f32 v[218:219], v[6:7], v[234:235], v[218:219]
	v_pk_fma_f32 v[216:217], v[4:5], v[232:233], v[216:217]
	v_pk_fma_f32 v[222:223], v[2:3], v[238:239], v[222:223]
	v_pk_fma_f32 v[220:221], v[0:1], v[236:237], v[220:221]
	global_store_dwordx4 v250, v[216:219], s[26:27] offset:512
	global_store_dwordx4 v250, v[220:223], s[26:27] offset:528
	s_branch .LBB0_655

.LBB0_1074:
	s_add_i32 s5, s4, 0x10000
	s_and_b32 s40, s5, 0x10000
	s_waitcnt vmcnt(0)
	s_barrier
	s_and_b32 s4, s4, 0x10000
	s_add_i32 s4, s4, 0
	v_add_u32_e32 v147, s4, v144
	v_add_u32_e32 v160, v147, v143
	ds_read_b128 v[148:151], v160
	ds_read_b128 v[152:155], v160 offset:2048
	ds_read_b128 v[156:159], v160 offset:4096
	ds_read_b128 v[170:173], v160 offset:6144
	v_add_u32_e32 v251, v147, v142
	v_add_u32_e32 v160, s4, v145
	v_add_u32_e32 v161, v160, v143
	ds_read_b128 v[178:181], v161 offset:32768
	ds_read_b128 v[182:185], v161 offset:34816
	ds_read_b128 v[186:189], v161 offset:36864
	ds_read_b128 v[192:195], v161 offset:38912
	v_add_u32_e32 v250, v160, v142
	ds_read_b128 v[216:219], v161 offset:40960
	ds_read_b128 v[220:223], v161 offset:43008
	ds_read_b128 v[224:227], v161 offset:45056
	ds_read_b128 v[228:231], v161 offset:47104
	v_add_u32_e32 v254, s40, v146
	v_add_u32_e32 v232, 0x2000, v254
	v_readfirstlane_b32 s40, v254
	v_lshl_add_u64 v[174:175], v[136:137], 0, s[2:3]
	s_mov_b32 m0, s40
	v_readfirstlane_b32 s40, v232
	v_add_u32_e32 v232, 0x4000, v254
	global_load_lds_dwordx4 v[174:175], off
	v_lshl_add_u64 v[174:175], v[134:135], 0, s[2:3]
	s_mov_b32 m0, s40
	s_waitcnt lgkmcnt(4)
	v_mfma_f32_16x16x32_bf16 v[124:127], v[148:151], v[178:181], v[124:127]
	ds_read_b128 v[198:201], v251
	v_mfma_f32_16x16x32_bf16 v[120:123], v[148:151], v[182:185], v[120:123]
	ds_read_b128 v[204:207], v251 offset:2048
	v_readfirstlane_b32 s40, v232
	v_add_u32_e32 v232, 0x6000, v254
	v_mfma_f32_16x16x32_bf16 v[116:119], v[148:151], v[186:189], v[116:119]
	ds_read_b128 v[208:211], v251 offset:4096
	global_load_lds_dwordx4 v[174:175], off
	v_lshl_add_u64 v[174:175], v[132:133], 0, s[2:3]
	v_mfma_f32_16x16x32_bf16 v[112:115], v[148:151], v[192:195], v[112:115]
	ds_read_b128 v[212:215], v251 offset:6144
	s_mov_b32 m0, s40
	v_readfirstlane_b32 s40, v232
	v_mfma_f32_16x16x32_bf16 v[104:107], v[152:155], v[178:181], v[104:107]
	global_load_lds_dwordx4 v[174:175], off
	v_lshl_add_u64 v[174:175], v[130:131], 0, s[2:3]
	v_mfma_f32_16x16x32_bf16 v[96:99], v[152:155], v[182:185], v[96:99]
	s_mov_b32 m0, s40
	s_mov_b64 s[40:41], 0x770080
	v_mfma_f32_16x16x32_bf16 v[88:91], v[152:155], v[186:189], v[88:91]
	global_load_lds_dwordx4 v[174:175], off
	v_lshl_add_u64 v[174:175], v[128:129], 0, s[2:3]
	v_mfma_f32_16x16x32_bf16 v[80:83], v[152:155], v[192:195], v[80:83]
	v_add_u32_e32 v253, 0x8000, v254
	v_lshl_add_u64 v[232:233], v[174:175], 0, s[40:41]
	v_mfma_f32_16x16x32_bf16 v[72:75], v[156:159], v[178:181], v[72:75]
	v_readfirstlane_b32 s40, v253
	s_mov_b32 m0, s40
	v_mfma_f32_16x16x32_bf16 v[64:67], v[156:159], v[182:185], v[64:67]
	s_mov_b64 s[40:41], 0x792080
	v_add_u32_e32 v253, 0xa000, v254
	v_mfma_f32_16x16x32_bf16 v[56:59], v[156:159], v[186:189], v[56:59]
	global_load_lds_dwordx4 v[232:233], off
	v_lshl_add_u64 v[232:233], v[174:175], 0, s[40:41]
	v_mfma_f32_16x16x32_bf16 v[48:51], v[156:159], v[192:195], v[48:51]
	v_readfirstlane_b32 s40, v253
	s_mov_b32 m0, s40
	v_mfma_f32_16x16x32_bf16 v[40:43], v[170:173], v[178:181], v[40:43]
	s_mov_b64 s[40:41], 0x7b4080
	v_add_u32_e32 v253, 0xc000, v254
	v_mfma_f32_16x16x32_bf16 v[32:35], v[170:173], v[182:185], v[32:35]
	global_load_lds_dwordx4 v[232:233], off
	v_lshl_add_u64 v[232:233], v[174:175], 0, s[40:41]
	v_mfma_f32_16x16x32_bf16 v[24:27], v[170:173], v[186:189], v[24:27]
	v_readfirstlane_b32 s40, v253
	s_mov_b32 m0, s40
	v_mfma_f32_16x16x32_bf16 v[16:19], v[170:173], v[192:195], v[16:19]
	s_mov_b64 s[40:41], 0x7d6080
	v_add_u32_e32 v254, 0xe000, v254
	s_waitcnt lgkmcnt(4)
	v_mfma_f32_16x16x32_bf16 v[100:103], v[148:151], v[216:219], v[100:103]
	v_lshl_add_u64 v[174:175], v[174:175], 0, s[40:41]
	v_readfirstlane_b32 s40, v254
	v_mfma_f32_16x16x32_bf16 v[92:95], v[148:151], v[220:223], v[92:95]
	global_load_lds_dwordx4 v[232:233], off
	s_mov_b32 m0, s40
	v_mfma_f32_16x16x32_bf16 v[84:87], v[148:151], v[224:227], v[84:87]
	ds_read_b128 v[178:181], v250 offset:32768
	global_load_lds_dwordx4 v[174:175], off
	v_mfma_f32_16x16x32_bf16 v[76:79], v[148:151], v[228:231], v[76:79]
	ds_read_b128 v[182:185], v250 offset:34816
	v_mfma_f32_16x16x32_bf16 v[68:71], v[152:155], v[216:219], v[68:71]
	ds_read_b128 v[186:189], v250 offset:36864
	v_mfma_f32_16x16x32_bf16 v[60:63], v[152:155], v[220:223], v[60:63]
	ds_read_b128 v[192:195], v250 offset:38912
	v_mfma_f32_16x16x32_bf16 v[52:55], v[152:155], v[224:227], v[52:55]
	v_mfma_f32_16x16x32_bf16 v[44:47], v[152:155], v[228:231], v[44:47]
	v_mfma_f32_16x16x32_bf16 v[36:39], v[156:159], v[216:219], v[36:39]
	v_mfma_f32_16x16x32_bf16 v[28:31], v[156:159], v[220:223], v[28:31]
	v_mfma_f32_16x16x32_bf16 v[20:23], v[156:159], v[224:227], v[20:23]
	v_mfma_f32_16x16x32_bf16 v[12:15], v[156:159], v[228:231], v[12:15]
	v_mfma_f32_16x16x32_bf16 v[8:11], v[170:173], v[216:219], v[8:11]
	v_mfma_f32_16x16x32_bf16 v[4:7], v[170:173], v[220:223], v[4:7]
	v_mfma_f32_16x16x32_bf16 v[0:3], v[170:173], v[224:227], v[0:3]
	v_mfma_f32_16x16x32_bf16 v[108:111], v[170:173], v[228:231], v[108:111]
	s_waitcnt lgkmcnt(0)
	v_mfma_f32_16x16x32_bf16 v[124:127], v[198:201], v[178:181], v[124:127]
	ds_read_b128 v[216:219], v250 offset:40960
	v_mfma_f32_16x16x32_bf16 v[120:123], v[198:201], v[182:185], v[120:123]
	ds_read_b128 v[220:223], v250 offset:43008
	v_mfma_f32_16x16x32_bf16 v[116:119], v[198:201], v[186:189], v[116:119]
	ds_read_b128 v[224:227], v250 offset:45056
	v_mfma_f32_16x16x32_bf16 v[112:115], v[198:201], v[192:195], v[112:115]
	ds_read_b128 v[228:231], v250 offset:47104
	v_mfma_f32_16x16x32_bf16 v[104:107], v[204:207], v[178:181], v[104:107]
	v_mfma_f32_16x16x32_bf16 v[96:99], v[204:207], v[182:185], v[96:99]
	v_mfma_f32_16x16x32_bf16 v[88:91], v[204:207], v[186:189], v[88:91]
	v_mfma_f32_16x16x32_bf16 v[80:83], v[204:207], v[192:195], v[80:83]
	v_mfma_f32_16x16x32_bf16 v[72:75], v[208:211], v[178:181], v[72:75]
	v_mfma_f32_16x16x32_bf16 v[64:67], v[208:211], v[182:185], v[64:67]
	v_mfma_f32_16x16x32_bf16 v[56:59], v[208:211], v[186:189], v[56:59]
	v_mfma_f32_16x16x32_bf16 v[48:51], v[208:211], v[192:195], v[48:51]
	v_mfma_f32_16x16x32_bf16 v[40:43], v[212:215], v[178:181], v[40:43]
	v_mfma_f32_16x16x32_bf16 v[32:35], v[212:215], v[182:185], v[32:35]
	v_mfma_f32_16x16x32_bf16 v[24:27], v[212:215], v[186:189], v[24:27]
	v_mfma_f32_16x16x32_bf16 v[16:19], v[212:215], v[192:195], v[16:19]
	s_waitcnt lgkmcnt(0)
	v_mfma_f32_16x16x32_bf16 v[100:103], v[198:201], v[216:219], v[100:103]
	v_mfma_f32_16x16x32_bf16 v[92:95], v[198:201], v[220:223], v[92:95]
	v_mfma_f32_16x16x32_bf16 v[84:87], v[198:201], v[224:227], v[84:87]
	v_mfma_f32_16x16x32_bf16 v[76:79], v[198:201], v[228:231], v[76:79]
	v_mfma_f32_16x16x32_bf16 v[68:71], v[204:207], v[216:219], v[68:71]
	v_mfma_f32_16x16x32_bf16 v[60:63], v[204:207], v[220:223], v[60:63]
	v_mfma_f32_16x16x32_bf16 v[52:55], v[204:207], v[224:227], v[52:55]
	v_mfma_f32_16x16x32_bf16 v[44:47], v[204:207], v[228:231], v[44:47]
	v_mfma_f32_16x16x32_bf16 v[36:39], v[208:211], v[216:219], v[36:39]
	v_mfma_f32_16x16x32_bf16 v[28:31], v[208:211], v[220:223], v[28:31]
	v_mfma_f32_16x16x32_bf16 v[20:23], v[208:211], v[224:227], v[20:23]
	v_mfma_f32_16x16x32_bf16 v[12:15], v[208:211], v[228:231], v[12:15]
	s_add_u32 s2, s2, 0x80
	s_addc_u32 s3, s3, 0
	s_cmpk_eq_i32 s2, 0x780
	s_mov_b32 s4, s5
	v_mfma_f32_16x16x32_bf16 v[8:11], v[212:215], v[216:219], v[8:11]
	v_mfma_f32_16x16x32_bf16 v[4:7], v[212:215], v[220:223], v[4:7]
	v_mfma_f32_16x16x32_bf16 v[0:3], v[212:215], v[224:227], v[0:3]
	v_mfma_f32_16x16x32_bf16 v[108:111], v[212:215], v[228:231], v[108:111]
	s_cbranch_scc0 .LBB0_1074
	s_add_i32 s2, 0, 0x10000
	v_add_u32_e32 v136, s2, v145
	v_add_u32_e32 v174, s2, v144
	v_add_u32_e32 v137, v136, v143
	v_add_u32_e32 v143, v174, v143
	s_waitcnt vmcnt(0)
	s_barrier
	ds_read_b128 v[128:131], v137 offset:38912
	ds_read_b128 v[132:135], v137 offset:36864
	ds_read_b128 v[146:149], v137 offset:34816
	ds_read_b128 v[150:153], v137 offset:32768
	ds_read_b128 v[154:157], v143 offset:6144
	ds_read_b128 v[158:161], v143 offset:4096
	ds_read_b128 v[170:173], v143 offset:2048
	ds_read_b128 v[178:181], v143
	s_waitcnt lgkmcnt(0)
	v_mfma_f32_16x16x32_bf16 v[124:127], v[178:181], v[150:153], v[124:127]
	v_mfma_f32_16x16x32_bf16 v[120:123], v[178:181], v[146:149], v[120:123]
	v_mfma_f32_16x16x32_bf16 v[116:119], v[178:181], v[132:135], v[116:119]
	v_mfma_f32_16x16x32_bf16 v[112:115], v[178:181], v[128:131], v[112:115]
	v_mfma_f32_16x16x32_bf16 v[104:107], v[170:173], v[150:153], v[104:107]
	v_mfma_f32_16x16x32_bf16 v[72:75], v[158:161], v[150:153], v[72:75]
	v_mfma_f32_16x16x32_bf16 v[64:67], v[158:161], v[146:149], v[64:67]
	v_mfma_f32_16x16x32_bf16 v[56:59], v[158:161], v[132:135], v[56:59]
	v_mfma_f32_16x16x32_bf16 v[48:51], v[158:161], v[128:131], v[48:51]
	v_mfma_f32_16x16x32_bf16 v[182:185], v[170:173], v[146:149], v[96:99]
	v_mfma_f32_16x16x32_bf16 v[186:189], v[170:173], v[132:135], v[88:91]
	v_mfma_f32_16x16x32_bf16 v[192:195], v[170:173], v[128:131], v[80:83]
	v_mfma_f32_16x16x32_bf16 v[150:153], v[154:157], v[150:153], v[40:43]
	v_mfma_f32_16x16x32_bf16 v[144:147], v[154:157], v[146:149], v[32:35]
	v_mfma_f32_16x16x32_bf16 v[132:135], v[154:157], v[132:135], v[24:27]
	v_mfma_f32_16x16x32_bf16 v[128:131], v[154:157], v[128:131], v[16:19]
	s_nop 2
	ds_read_b128 v[16:19], v137 offset:40960
	ds_read_b128 v[24:27], v137 offset:43008
	ds_read_b128 v[32:35], v137 offset:45056
	ds_read_b128 v[40:43], v137 offset:47104
	s_waitcnt lgkmcnt(0)
	v_mfma_f32_16x16x32_bf16 v[100:103], v[178:181], v[16:19], v[100:103]
	v_mfma_f32_16x16x32_bf16 v[92:95], v[178:181], v[24:27], v[92:95]
	v_mfma_f32_16x16x32_bf16 v[198:201], v[178:181], v[32:35], v[84:87]
	v_mfma_f32_16x16x32_bf16 v[76:79], v[178:181], v[40:43], v[76:79]
	v_mfma_f32_16x16x32_bf16 v[68:71], v[170:173], v[16:19], v[68:71]
	v_mfma_f32_16x16x32_bf16 v[60:63], v[170:173], v[24:27], v[60:63]
	v_mfma_f32_16x16x32_bf16 v[178:181], v[170:173], v[32:35], v[52:55]
	v_mfma_f32_16x16x32_bf16 v[44:47], v[170:173], v[40:43], v[44:47]
	v_mfma_f32_16x16x32_bf16 v[170:173], v[158:161], v[16:19], v[36:39]
	v_mfma_f32_16x16x32_bf16 v[204:207], v[158:161], v[24:27], v[28:31]
	v_mfma_f32_16x16x32_bf16 v[208:211], v[158:161], v[32:35], v[20:23]
	v_mfma_f32_16x16x32_bf16 v[158:161], v[158:161], v[40:43], v[12:15]
	v_mfma_f32_16x16x32_bf16 v[212:215], v[154:157], v[16:19], v[8:11]
	v_mfma_f32_16x16x32_bf16 v[216:219], v[154:157], v[24:27], v[4:7]
	v_mfma_f32_16x16x32_bf16 v[220:223], v[154:157], v[32:35], v[0:3]
	v_mfma_f32_16x16x32_bf16 v[154:157], v[154:157], v[40:43], v[108:111]
	s_nop 1
	v_add_u32_e32 v0, v174, v142
	v_add_u32_e32 v136, v136, v142
	ds_read_b128 v[108:111], v0
	ds_read_b128 v[224:227], v0 offset:2048
	ds_read_b128 v[228:231], v0 offset:4096
	ds_read_b128 v[232:235], v0 offset:6144
	ds_read_b128 v[0:3], v136 offset:32768
	ds_read_b128 v[4:7], v136 offset:34816
	ds_read_b128 v[236:239], v136 offset:36864
	ds_read_b128 v[240:243], v136 offset:38912
	s_waitcnt lgkmcnt(0)
	v_mfma_f32_16x16x32_bf16 v[88:91], v[108:111], v[0:3], v[124:127]
	v_mfma_f32_16x16x32_bf16 v[96:99], v[108:111], v[4:7], v[120:123]
	v_mfma_f32_16x16x32_bf16 v[80:83], v[108:111], v[236:239], v[116:119]
	v_mfma_f32_16x16x32_bf16 v[84:87], v[108:111], v[240:243], v[112:115]
	v_mfma_f32_16x16x32_bf16 v[40:43], v[224:227], v[0:3], v[104:107]
	v_mfma_f32_16x16x32_bf16 v[52:55], v[224:227], v[4:7], v[182:185]
	v_mfma_f32_16x16x32_bf16 v[32:35], v[224:227], v[236:239], v[186:189]
	v_mfma_f32_16x16x32_bf16 v[36:39], v[224:227], v[240:243], v[192:195]
	v_mfma_f32_16x16x32_bf16 v[24:27], v[228:231], v[0:3], v[72:75]
	v_mfma_f32_16x16x32_bf16 v[28:31], v[228:231], v[4:7], v[64:67]
	v_mfma_f32_16x16x32_bf16 v[16:19], v[228:231], v[236:239], v[56:59]
	v_mfma_f32_16x16x32_bf16 v[20:23], v[228:231], v[240:243], v[48:51]
	v_mfma_f32_16x16x32_bf16 v[8:11], v[232:235], v[0:3], v[150:153]
	v_mfma_f32_16x16x32_bf16 v[12:15], v[232:235], v[4:7], v[144:147]
	v_mfma_f32_16x16x32_bf16 v[0:3], v[232:235], v[236:239], v[132:135]
	v_mfma_f32_16x16x32_bf16 v[4:7], v[232:235], v[240:243], v[128:131]
	ds_read_b128 v[48:51], v136 offset:40960
	ds_read_b128 v[64:67], v136 offset:43008
	s_nop 0
	ds_read_b128 v[128:131], v136 offset:45056
	ds_read_b128 v[132:135], v136 offset:47104
	s_waitcnt lgkmcnt(0)
	v_mfma_f32_16x16x32_bf16 v[104:107], v[224:227], v[48:51], v[68:71]
	v_cmp_ne_u32_e32 vcc, 0, v138
	v_cmp_eq_u32_e64 s[2:3], 0, v138
	s_waitcnt vmcnt(0)
	v_lshl_or_b32 v68, v140, 2, v141
	v_lshl_add_u32 v69, v139, 2, 0
	v_mfma_f32_16x16x32_bf16 v[120:123], v[108:111], v[48:51], v[100:103]
	s_barrier
	v_mfma_f32_16x16x32_bf16 v[124:127], v[108:111], v[64:67], v[92:95]
	v_mfma_f32_16x16x32_bf16 v[112:115], v[108:111], v[128:131], v[198:201]
	v_mfma_f32_16x16x32_bf16 v[116:119], v[108:111], v[132:135], v[76:79]
	v_mfma_f32_16x16x32_bf16 v[108:111], v[224:227], v[64:67], v[60:63]
	v_mfma_f32_16x16x32_bf16 v[92:95], v[224:227], v[128:131], v[178:181]
	v_mfma_f32_16x16x32_bf16 v[100:103], v[224:227], v[132:135], v[44:47]
	s_nop 1
	v_lshl_add_u32 v178, v68, 9, v69
	v_add_u32_e32 v179, 0x400, v178
	v_add_u32_e32 v176, 0x2000, v178
	v_mfma_f32_16x16x32_bf16 v[56:59], v[228:231], v[48:51], v[170:173]
	v_add_u32_e32 v175, 0x2400, v178
	v_add_u32_e32 v174, 0x4000, v178
	v_mfma_f32_16x16x32_bf16 v[60:63], v[228:231], v[64:67], v[204:207]
	v_add_u32_e32 v173, 0x4400, v178
	v_add_u32_e32 v172, 0x6000, v178
	v_add_u32_e32 v171, 0x6400, v178
	v_mfma_f32_16x16x32_bf16 v[44:47], v[228:231], v[128:131], v[208:211]
	v_mfma_f32_16x16x32_bf16 v[72:75], v[228:231], v[132:135], v[158:161]
	v_mfma_f32_16x16x32_bf16 v[48:51], v[232:235], v[48:51], v[212:215]
	v_mfma_f32_16x16x32_bf16 v[64:67], v[232:235], v[64:67], v[216:219]
	v_mfma_f32_16x16x32_bf16 v[68:71], v[232:235], v[128:131], v[220:223]
	v_mfma_f32_16x16x32_bf16 v[76:79], v[232:235], v[132:135], v[154:157]
	s_and_saveexec_b64 s[4:5], s[2:3]
	s_cbranch_execz .LBB0_1077
	ds_write2_b32 v178, v88, v96 offset1:16
	ds_write2_b32 v178, v89, v97 offset0:128 offset1:144
	ds_write2_b32 v179, v90, v98 offset1:16
	ds_write2_b32 v179, v91, v99 offset0:128 offset1:144
	ds_write2_b32 v178, v80, v84 offset0:32 offset1:48
	ds_write2_b32 v178, v81, v85 offset0:160 offset1:176
	ds_write2_b32 v179, v82, v86 offset0:32 offset1:48
	ds_write2_b32 v179, v83, v87 offset0:160 offset1:176
	ds_write2_b32 v178, v120, v124 offset0:64 offset1:80
	ds_write2_b32 v178, v121, v125 offset0:192 offset1:208
	ds_write2_b32 v179, v122, v126 offset0:64 offset1:80
	ds_write2_b32 v179, v123, v127 offset0:192 offset1:208
	ds_write2_b32 v178, v112, v116 offset0:96 offset1:112
	ds_write2_b32 v178, v113, v117 offset0:224 offset1:240
	ds_write2_b32 v179, v114, v118 offset0:96 offset1:112
	ds_write2_b32 v179, v115, v119 offset0:224 offset1:240
	ds_write2_b32 v176, v40, v52 offset1:16
	ds_write2_b32 v176, v41, v53 offset0:128 offset1:144
	ds_write2_b32 v175, v42, v54 offset1:16
	ds_write2_b32 v175, v43, v55 offset0:128 offset1:144
	ds_write2_b32 v176, v32, v36 offset0:32 offset1:48
	ds_write2_b32 v176, v33, v37 offset0:160 offset1:176
	ds_write2_b32 v175, v34, v38 offset0:32 offset1:48
	ds_write2_b32 v175, v35, v39 offset0:160 offset1:176
	ds_write2_b32 v176, v104, v108 offset0:64 offset1:80
	ds_write2_b32 v176, v105, v109 offset0:192 offset1:208
	ds_write2_b32 v175, v106, v110 offset0:64 offset1:80
	ds_write2_b32 v175, v107, v111 offset0:192 offset1:208
	ds_write2_b32 v176, v92, v100 offset0:96 offset1:112
	ds_write2_b32 v176, v93, v101 offset0:224 offset1:240
	ds_write2_b32 v175, v94, v102 offset0:96 offset1:112
	ds_write2_b32 v175, v95, v103 offset0:224 offset1:240
	ds_write2_b32 v174, v24, v28 offset1:16
	ds_write2_b32 v174, v25, v29 offset0:128 offset1:144
	ds_write2_b32 v173, v26, v30 offset1:16
	ds_write2_b32 v173, v27, v31 offset0:128 offset1:144
	ds_write2_b32 v174, v16, v20 offset0:32 offset1:48
	ds_write2_b32 v174, v17, v21 offset0:160 offset1:176
	ds_write2_b32 v173, v18, v22 offset0:32 offset1:48
	ds_write2_b32 v173, v19, v23 offset0:160 offset1:176
	ds_write2_b32 v174, v56, v60 offset0:64 offset1:80
	ds_write2_b32 v174, v57, v61 offset0:192 offset1:208
	ds_write2_b32 v173, v58, v62 offset0:64 offset1:80
	ds_write2_b32 v173, v59, v63 offset0:192 offset1:208
	ds_write2_b32 v174, v44, v72 offset0:96 offset1:112
	ds_write2_b32 v174, v45, v73 offset0:224 offset1:240
	ds_write2_b32 v173, v46, v74 offset0:96 offset1:112
	ds_write2_b32 v173, v47, v75 offset0:224 offset1:240
	ds_write2_b32 v172, v8, v12 offset1:16
	ds_write2_b32 v172, v9, v13 offset0:128 offset1:144
	ds_write2_b32 v171, v10, v14 offset1:16
	ds_write2_b32 v171, v11, v15 offset0:128 offset1:144
	ds_write2_b32 v172, v0, v4 offset0:32 offset1:48
	ds_write2_b32 v172, v1, v5 offset0:160 offset1:176
	ds_write2_b32 v171, v2, v6 offset0:32 offset1:48
	ds_write2_b32 v171, v3, v7 offset0:160 offset1:176
	ds_write2_b32 v172, v48, v64 offset0:64 offset1:80
	ds_write2_b32 v172, v49, v65 offset0:192 offset1:208
	ds_write2_b32 v171, v50, v66 offset0:64 offset1:80
	ds_write2_b32 v171, v51, v67 offset0:192 offset1:208
	ds_write2_b32 v172, v68, v76 offset0:96 offset1:112
	ds_write2_b32 v172, v69, v77 offset0:224 offset1:240
	ds_write2_b32 v171, v70, v78 offset0:96 offset1:112
	ds_write2_b32 v171, v71, v79 offset0:224 offset1:240

.LBB0_1143:
	s_add_i32 s11, s10, 0x10000
	s_and_b32 s19, s11, 0x10000
	s_waitcnt vmcnt(0)
	s_barrier
	s_and_b32 s10, s10, 0x10000
	s_add_i32 s10, s10, 0
	v_add_u32_e32 v151, s10, v149
	v_add_u32_e32 v164, v151, v147
	ds_read_b128 v[152:155], v164
	ds_read_b128 v[156:159], v164 offset:2048
	ds_read_b128 v[160:163], v164 offset:4096
	ds_read_b128 v[164:167], v164 offset:6144
	v_add_u32_e32 v251, v151, v146
	v_add_u32_e32 v176, s10, v148
	v_add_u32_e32 v186, v176, v147
	ds_read_b128 v[168:171], v186 offset:32768
	ds_read_b128 v[172:175], v186 offset:34816
	ds_read_b128 v[178:181], v186 offset:36864
	ds_read_b128 v[182:185], v186 offset:38912
	v_add_u32_e32 v250, v176, v146
	ds_read_b128 v[212:215], v186 offset:40960
	ds_read_b128 v[216:219], v186 offset:43008
	ds_read_b128 v[220:223], v186 offset:45056
	ds_read_b128 v[224:227], v186 offset:47104
	v_add_u32_e32 v254, s19, v150
	v_add_u32_e32 v228, 0x2000, v254
	v_readfirstlane_b32 s19, v254
	v_lshl_add_u64 v[188:189], v[128:129], 0, s[2:3]
	s_mov_b32 m0, s19
	v_readfirstlane_b32 s19, v228
	v_add_u32_e32 v228, 0x4000, v254
	global_load_lds_dwordx4 v[188:189], off
	v_lshl_add_u64 v[188:189], v[130:131], 0, s[2:3]
	s_mov_b32 m0, s19
	s_waitcnt lgkmcnt(4)
	v_mfma_f32_16x16x32_bf16 v[124:127], v[152:155], v[168:171], v[124:127]
	ds_read_b128 v[192:195], v251
	v_mfma_f32_16x16x32_bf16 v[120:123], v[152:155], v[172:175], v[120:123]
	ds_read_b128 v[198:201], v251 offset:2048
	v_readfirstlane_b32 s19, v228
	v_add_u32_e32 v228, 0x6000, v254
	v_mfma_f32_16x16x32_bf16 v[116:119], v[152:155], v[178:181], v[116:119]
	ds_read_b128 v[204:207], v251 offset:4096
	global_load_lds_dwordx4 v[188:189], off
	v_lshl_add_u64 v[188:189], v[132:133], 0, s[2:3]
	v_mfma_f32_16x16x32_bf16 v[112:115], v[152:155], v[182:185], v[112:115]
	ds_read_b128 v[208:211], v251 offset:6144
	s_mov_b32 m0, s19
	v_readfirstlane_b32 s19, v228
	v_mfma_f32_16x16x32_bf16 v[104:107], v[156:159], v[168:171], v[104:107]
	global_load_lds_dwordx4 v[188:189], off
	v_lshl_add_u64 v[188:189], v[134:135], 0, s[2:3]
	v_mfma_f32_16x16x32_bf16 v[96:99], v[156:159], v[172:175], v[96:99]
	s_mov_b32 m0, s19
	v_add_u32_e32 v253, 0x8000, v254
	v_mfma_f32_16x16x32_bf16 v[88:91], v[156:159], v[178:181], v[88:91]
	global_load_lds_dwordx4 v[188:189], off
	v_lshl_add_u64 v[188:189], v[136:137], 0, s[2:3]
	v_mfma_f32_16x16x32_bf16 v[80:83], v[156:159], v[182:185], v[80:83]
	s_mov_b64 s[20:21], 0x1320080
	v_readfirstlane_b32 s19, v253
	v_mfma_f32_16x16x32_bf16 v[72:75], v[160:163], v[168:171], v[72:75]
	v_add_u32_e32 v253, 0xa000, v254
	v_lshl_add_u64 v[228:229], v[188:189], 0, s[20:21]
	v_mfma_f32_16x16x32_bf16 v[64:67], v[160:163], v[172:175], v[64:67]
	s_mov_b32 m0, s19
	s_mov_b64 s[20:21], 0x1378080
	v_mfma_f32_16x16x32_bf16 v[56:59], v[160:163], v[178:181], v[56:59]
	v_readfirstlane_b32 s19, v253
	v_add_u32_e32 v253, 0xc000, v254
	v_mfma_f32_16x16x32_bf16 v[48:51], v[160:163], v[182:185], v[48:51]
	global_load_lds_dwordx4 v[228:229], off
	v_lshl_add_u64 v[228:229], v[188:189], 0, s[20:21]
	v_mfma_f32_16x16x32_bf16 v[40:43], v[164:167], v[168:171], v[40:43]
	s_mov_b32 m0, s19
	s_mov_b64 s[20:21], 0x13d0080
	v_mfma_f32_16x16x32_bf16 v[32:35], v[164:167], v[172:175], v[32:35]
	v_readfirstlane_b32 s19, v253
	v_add_u32_e32 v254, 0xe000, v254
	v_mfma_f32_16x16x32_bf16 v[24:27], v[164:167], v[178:181], v[24:27]
	global_load_lds_dwordx4 v[228:229], off
	v_lshl_add_u64 v[228:229], v[188:189], 0, s[20:21]
	v_mfma_f32_16x16x32_bf16 v[16:19], v[164:167], v[182:185], v[16:19]
	s_mov_b32 m0, s19
	s_mov_b64 s[20:21], 0x1428080
	s_waitcnt lgkmcnt(4)
	v_mfma_f32_16x16x32_bf16 v[100:103], v[152:155], v[212:215], v[100:103]
	v_readfirstlane_b32 s19, v254
	global_load_lds_dwordx4 v[228:229], off
	v_mfma_f32_16x16x32_bf16 v[92:95], v[152:155], v[216:219], v[92:95]
	v_lshl_add_u64 v[188:189], v[188:189], 0, s[20:21]
	s_mov_b32 m0, s19
	v_mfma_f32_16x16x32_bf16 v[84:87], v[152:155], v[220:223], v[84:87]
	ds_read_b128 v[168:171], v250 offset:32768
	global_load_lds_dwordx4 v[188:189], off
	v_mfma_f32_16x16x32_bf16 v[76:79], v[152:155], v[224:227], v[76:79]
	ds_read_b128 v[172:175], v250 offset:34816
	v_mfma_f32_16x16x32_bf16 v[68:71], v[156:159], v[212:215], v[68:71]
	ds_read_b128 v[178:181], v250 offset:36864
	v_mfma_f32_16x16x32_bf16 v[60:63], v[156:159], v[216:219], v[60:63]
	ds_read_b128 v[182:185], v250 offset:38912
	v_mfma_f32_16x16x32_bf16 v[52:55], v[156:159], v[220:223], v[52:55]
	v_mfma_f32_16x16x32_bf16 v[44:47], v[156:159], v[224:227], v[44:47]
	v_mfma_f32_16x16x32_bf16 v[36:39], v[160:163], v[212:215], v[36:39]
	v_mfma_f32_16x16x32_bf16 v[28:31], v[160:163], v[216:219], v[28:31]
	v_mfma_f32_16x16x32_bf16 v[20:23], v[160:163], v[220:223], v[20:23]
	v_mfma_f32_16x16x32_bf16 v[12:15], v[160:163], v[224:227], v[12:15]
	v_mfma_f32_16x16x32_bf16 v[8:11], v[164:167], v[212:215], v[8:11]
	v_mfma_f32_16x16x32_bf16 v[4:7], v[164:167], v[216:219], v[4:7]
	v_mfma_f32_16x16x32_bf16 v[0:3], v[164:167], v[220:223], v[0:3]
	v_mfma_f32_16x16x32_bf16 v[108:111], v[164:167], v[224:227], v[108:111]
	s_waitcnt lgkmcnt(0)
	v_mfma_f32_16x16x32_bf16 v[124:127], v[192:195], v[168:171], v[124:127]
	ds_read_b128 v[212:215], v250 offset:40960
	v_mfma_f32_16x16x32_bf16 v[120:123], v[192:195], v[172:175], v[120:123]
	ds_read_b128 v[216:219], v250 offset:43008
	v_mfma_f32_16x16x32_bf16 v[116:119], v[192:195], v[178:181], v[116:119]
	ds_read_b128 v[220:223], v250 offset:45056
	v_mfma_f32_16x16x32_bf16 v[112:115], v[192:195], v[182:185], v[112:115]
	ds_read_b128 v[224:227], v250 offset:47104
	v_mfma_f32_16x16x32_bf16 v[104:107], v[198:201], v[168:171], v[104:107]
	v_mfma_f32_16x16x32_bf16 v[96:99], v[198:201], v[172:175], v[96:99]
	v_mfma_f32_16x16x32_bf16 v[88:91], v[198:201], v[178:181], v[88:91]
	v_mfma_f32_16x16x32_bf16 v[80:83], v[198:201], v[182:185], v[80:83]
	v_mfma_f32_16x16x32_bf16 v[72:75], v[204:207], v[168:171], v[72:75]
	v_mfma_f32_16x16x32_bf16 v[64:67], v[204:207], v[172:175], v[64:67]
	v_mfma_f32_16x16x32_bf16 v[56:59], v[204:207], v[178:181], v[56:59]
	v_mfma_f32_16x16x32_bf16 v[48:51], v[204:207], v[182:185], v[48:51]
	v_mfma_f32_16x16x32_bf16 v[40:43], v[208:211], v[168:171], v[40:43]
	v_mfma_f32_16x16x32_bf16 v[32:35], v[208:211], v[172:175], v[32:35]
	v_mfma_f32_16x16x32_bf16 v[24:27], v[208:211], v[178:181], v[24:27]
	v_mfma_f32_16x16x32_bf16 v[16:19], v[208:211], v[182:185], v[16:19]
	s_waitcnt lgkmcnt(0)
	v_mfma_f32_16x16x32_bf16 v[100:103], v[192:195], v[212:215], v[100:103]
	v_mfma_f32_16x16x32_bf16 v[92:95], v[192:195], v[216:219], v[92:95]
	v_mfma_f32_16x16x32_bf16 v[84:87], v[192:195], v[220:223], v[84:87]
	v_mfma_f32_16x16x32_bf16 v[76:79], v[192:195], v[224:227], v[76:79]
	v_mfma_f32_16x16x32_bf16 v[68:71], v[198:201], v[212:215], v[68:71]
	v_mfma_f32_16x16x32_bf16 v[60:63], v[198:201], v[216:219], v[60:63]
	v_mfma_f32_16x16x32_bf16 v[52:55], v[198:201], v[220:223], v[52:55]
	v_mfma_f32_16x16x32_bf16 v[44:47], v[198:201], v[224:227], v[44:47]
	v_mfma_f32_16x16x32_bf16 v[36:39], v[204:207], v[212:215], v[36:39]
	v_mfma_f32_16x16x32_bf16 v[28:31], v[204:207], v[216:219], v[28:31]
	v_mfma_f32_16x16x32_bf16 v[20:23], v[204:207], v[220:223], v[20:23]
	v_mfma_f32_16x16x32_bf16 v[12:15], v[204:207], v[224:227], v[12:15]
	s_add_u32 s2, s2, 0x80
	s_addc_u32 s3, s3, 0
	s_cmpk_eq_i32 s2, 0x1580
	s_mov_b32 s10, s11
	v_mfma_f32_16x16x32_bf16 v[8:11], v[208:211], v[212:215], v[8:11]
	v_mfma_f32_16x16x32_bf16 v[4:7], v[208:211], v[216:219], v[4:7]
	v_mfma_f32_16x16x32_bf16 v[0:3], v[208:211], v[220:223], v[0:3]
	v_mfma_f32_16x16x32_bf16 v[108:111], v[208:211], v[224:227], v[108:111]
	s_cbranch_scc0 .LBB0_1143
	s_add_i32 s2, 0, 0x10000
	v_add_u32_e32 v136, s2, v149
	v_add_u32_e32 v137, v136, v147
	s_waitcnt vmcnt(0)
	s_barrier
	ds_read_b128 v[128:131], v137
	ds_read_b128 v[132:135], v137 offset:2048
	ds_read_b128 v[150:153], v137 offset:4096
	ds_read_b128 v[154:157], v137 offset:6144
	v_add_u32_e32 v137, s2, v148
	v_add_u32_e32 v147, v137, v147
	ds_read_b128 v[158:161], v147 offset:32768
	ds_read_b128 v[162:165], v147 offset:34816
	ds_read_b128 v[166:169], v147 offset:36864
	ds_read_b128 v[170:173], v147 offset:38912
	s_waitcnt lgkmcnt(0)
	v_mfma_f32_16x16x32_bf16 v[124:127], v[128:131], v[158:161], v[124:127]
	v_mfma_f32_16x16x32_bf16 v[120:123], v[128:131], v[162:165], v[120:123]
	v_mfma_f32_16x16x32_bf16 v[116:119], v[128:131], v[166:169], v[116:119]
	v_mfma_f32_16x16x32_bf16 v[112:115], v[128:131], v[170:173], v[112:115]
	v_mfma_f32_16x16x32_bf16 v[104:107], v[132:135], v[158:161], v[104:107]
	v_mfma_f32_16x16x32_bf16 v[72:75], v[150:153], v[158:161], v[72:75]
	v_mfma_f32_16x16x32_bf16 v[64:67], v[150:153], v[162:165], v[64:67]
	v_mfma_f32_16x16x32_bf16 v[56:59], v[150:153], v[166:169], v[56:59]
	v_mfma_f32_16x16x32_bf16 v[48:51], v[150:153], v[170:173], v[48:51]
	v_mfma_f32_16x16x32_bf16 v[178:181], v[132:135], v[162:165], v[96:99]
	v_mfma_f32_16x16x32_bf16 v[182:185], v[132:135], v[166:169], v[88:91]
	v_mfma_f32_16x16x32_bf16 v[186:189], v[132:135], v[170:173], v[80:83]
	v_mfma_f32_16x16x32_bf16 v[158:161], v[154:157], v[158:161], v[40:43]
	v_mfma_f32_16x16x32_bf16 v[162:165], v[154:157], v[162:165], v[32:35]
	v_mfma_f32_16x16x32_bf16 v[166:169], v[154:157], v[166:169], v[24:27]
	v_mfma_f32_16x16x32_bf16 v[170:173], v[154:157], v[170:173], v[16:19]
	s_nop 2
	ds_read_b128 v[16:19], v147 offset:40960
	ds_read_b128 v[24:27], v147 offset:43008
	ds_read_b128 v[32:35], v147 offset:45056
	ds_read_b128 v[40:43], v147 offset:47104
	s_waitcnt lgkmcnt(0)
	v_mfma_f32_16x16x32_bf16 v[100:103], v[128:131], v[16:19], v[100:103]
	v_mfma_f32_16x16x32_bf16 v[92:95], v[128:131], v[24:27], v[92:95]
	v_mfma_f32_16x16x32_bf16 v[192:195], v[128:131], v[32:35], v[84:87]
	v_mfma_f32_16x16x32_bf16 v[76:79], v[128:131], v[40:43], v[76:79]
	v_mfma_f32_16x16x32_bf16 v[68:71], v[132:135], v[16:19], v[68:71]
	v_mfma_f32_16x16x32_bf16 v[60:63], v[132:135], v[24:27], v[60:63]
	v_mfma_f32_16x16x32_bf16 v[128:131], v[132:135], v[32:35], v[52:55]
	v_mfma_f32_16x16x32_bf16 v[44:47], v[132:135], v[40:43], v[44:47]
	v_mfma_f32_16x16x32_bf16 v[132:135], v[150:153], v[16:19], v[36:39]
	v_mfma_f32_16x16x32_bf16 v[198:201], v[150:153], v[24:27], v[28:31]
	v_mfma_f32_16x16x32_bf16 v[204:207], v[150:153], v[32:35], v[20:23]
	v_mfma_f32_16x16x32_bf16 v[148:151], v[150:153], v[40:43], v[12:15]
	v_mfma_f32_16x16x32_bf16 v[208:211], v[154:157], v[16:19], v[8:11]
	v_mfma_f32_16x16x32_bf16 v[212:215], v[154:157], v[24:27], v[4:7]
	v_mfma_f32_16x16x32_bf16 v[216:219], v[154:157], v[32:35], v[0:3]
	v_mfma_f32_16x16x32_bf16 v[154:157], v[154:157], v[40:43], v[108:111]
	s_nop 1
	v_add_u32_e32 v0, v136, v146
	v_add_u32_e32 v136, v137, v146
	ds_read_b128 v[108:111], v0
	ds_read_b128 v[220:223], v0 offset:2048
	ds_read_b128 v[224:227], v0 offset:4096
	ds_read_b128 v[228:231], v0 offset:6144
	ds_read_b128 v[0:3], v136 offset:32768
	ds_read_b128 v[4:7], v136 offset:34816
	ds_read_b128 v[232:235], v136 offset:36864
	ds_read_b128 v[236:239], v136 offset:38912
	s_waitcnt lgkmcnt(0)
	v_mfma_f32_16x16x32_bf16 v[88:91], v[108:111], v[0:3], v[124:127]
	v_mfma_f32_16x16x32_bf16 v[96:99], v[108:111], v[4:7], v[120:123]
	v_mfma_f32_16x16x32_bf16 v[80:83], v[108:111], v[232:235], v[116:119]
	v_mfma_f32_16x16x32_bf16 v[84:87], v[108:111], v[236:239], v[112:115]
	v_mfma_f32_16x16x32_bf16 v[40:43], v[220:223], v[0:3], v[104:107]
	v_mfma_f32_16x16x32_bf16 v[52:55], v[220:223], v[4:7], v[178:181]
	v_mfma_f32_16x16x32_bf16 v[32:35], v[220:223], v[232:235], v[182:185]
	v_mfma_f32_16x16x32_bf16 v[36:39], v[220:223], v[236:239], v[186:189]
	v_mfma_f32_16x16x32_bf16 v[24:27], v[224:227], v[0:3], v[72:75]
	v_mfma_f32_16x16x32_bf16 v[28:31], v[224:227], v[4:7], v[64:67]
	v_mfma_f32_16x16x32_bf16 v[16:19], v[224:227], v[232:235], v[56:59]
	v_mfma_f32_16x16x32_bf16 v[20:23], v[224:227], v[236:239], v[48:51]
	v_mfma_f32_16x16x32_bf16 v[8:11], v[228:231], v[0:3], v[158:161]
	v_mfma_f32_16x16x32_bf16 v[12:15], v[228:231], v[4:7], v[162:165]
	v_mfma_f32_16x16x32_bf16 v[0:3], v[228:231], v[232:235], v[166:169]
	v_mfma_f32_16x16x32_bf16 v[4:7], v[228:231], v[236:239], v[170:173]
	ds_read_b128 v[48:51], v136 offset:40960
	ds_read_b128 v[64:67], v136 offset:43008
	ds_read_b128 v[158:161], v136 offset:45056
	ds_read_b128 v[162:165], v136 offset:47104
	s_waitcnt lgkmcnt(0)
	v_mfma_f32_16x16x32_bf16 v[104:107], v[220:223], v[48:51], v[68:71]
	v_cmp_ne_u32_e32 vcc, 0, v138
	v_cmp_eq_u32_e64 s[2:3], 0, v138
	s_waitcnt vmcnt(0)
	v_lshl_or_b32 v68, v140, 2, v141
	v_lshl_add_u32 v69, v139, 2, 0
	v_mfma_f32_16x16x32_bf16 v[120:123], v[108:111], v[48:51], v[100:103]
	v_lshl_add_u32 v152, v68, 9, v69
	v_add_u32_e32 v153, 0x400, v152
	v_add_u32_e32 v147, 0x6000, v152
	v_mfma_f32_16x16x32_bf16 v[124:127], v[108:111], v[64:67], v[92:95]
	v_add_u32_e32 v146, 0x6400, v152
	s_barrier
	v_mfma_f32_16x16x32_bf16 v[112:115], v[108:111], v[158:161], v[192:195]
	v_mfma_f32_16x16x32_bf16 v[116:119], v[108:111], v[162:165], v[76:79]
	v_mfma_f32_16x16x32_bf16 v[108:111], v[220:223], v[64:67], v[60:63]
	v_mfma_f32_16x16x32_bf16 v[92:95], v[220:223], v[158:161], v[128:131]
	v_mfma_f32_16x16x32_bf16 v[100:103], v[220:223], v[162:165], v[44:47]
	v_mfma_f32_16x16x32_bf16 v[56:59], v[224:227], v[48:51], v[132:135]
	v_mfma_f32_16x16x32_bf16 v[60:63], v[224:227], v[64:67], v[198:201]
	v_mfma_f32_16x16x32_bf16 v[44:47], v[224:227], v[158:161], v[204:207]
	v_mfma_f32_16x16x32_bf16 v[72:75], v[224:227], v[162:165], v[148:151]
	v_mfma_f32_16x16x32_bf16 v[48:51], v[228:231], v[48:51], v[208:211]
	s_nop 1
	v_add_u32_e32 v151, 0x2000, v152
	v_add_u32_e32 v150, 0x2400, v152
	v_add_u32_e32 v149, 0x4000, v152
	v_mfma_f32_16x16x32_bf16 v[64:67], v[228:231], v[64:67], v[212:215]
	v_add_u32_e32 v148, 0x4400, v152
	v_mfma_f32_16x16x32_bf16 v[68:71], v[228:231], v[158:161], v[216:219]
	v_mfma_f32_16x16x32_bf16 v[76:79], v[228:231], v[162:165], v[154:157]
	s_and_saveexec_b64 s[10:11], s[2:3]
	s_cbranch_execz .LBB0_1146
	ds_write2_b32 v152, v88, v96 offset1:16
	ds_write2_b32 v152, v89, v97 offset0:128 offset1:144
	ds_write2_b32 v153, v90, v98 offset1:16
	ds_write2_b32 v153, v91, v99 offset0:128 offset1:144
	ds_write2_b32 v152, v80, v84 offset0:32 offset1:48
	ds_write2_b32 v152, v81, v85 offset0:160 offset1:176
	ds_write2_b32 v153, v82, v86 offset0:32 offset1:48
	ds_write2_b32 v153, v83, v87 offset0:160 offset1:176
	ds_write2_b32 v152, v120, v124 offset0:64 offset1:80
	ds_write2_b32 v152, v121, v125 offset0:192 offset1:208
	ds_write2_b32 v153, v122, v126 offset0:64 offset1:80
	ds_write2_b32 v153, v123, v127 offset0:192 offset1:208
	ds_write2_b32 v152, v112, v116 offset0:96 offset1:112
	ds_write2_b32 v152, v113, v117 offset0:224 offset1:240
	ds_write2_b32 v153, v114, v118 offset0:96 offset1:112
	ds_write2_b32 v153, v115, v119 offset0:224 offset1:240
	ds_write2_b32 v151, v40, v52 offset1:16
	ds_write2_b32 v151, v41, v53 offset0:128 offset1:144
	ds_write2_b32 v150, v42, v54 offset1:16
	ds_write2_b32 v150, v43, v55 offset0:128 offset1:144
	ds_write2_b32 v151, v32, v36 offset0:32 offset1:48
	ds_write2_b32 v151, v33, v37 offset0:160 offset1:176
	ds_write2_b32 v150, v34, v38 offset0:32 offset1:48
	ds_write2_b32 v150, v35, v39 offset0:160 offset1:176
	ds_write2_b32 v151, v104, v108 offset0:64 offset1:80
	ds_write2_b32 v151, v105, v109 offset0:192 offset1:208
	ds_write2_b32 v150, v106, v110 offset0:64 offset1:80
	ds_write2_b32 v150, v107, v111 offset0:192 offset1:208
	ds_write2_b32 v151, v92, v100 offset0:96 offset1:112
	ds_write2_b32 v151, v93, v101 offset0:224 offset1:240
	ds_write2_b32 v150, v94, v102 offset0:96 offset1:112
	ds_write2_b32 v150, v95, v103 offset0:224 offset1:240
	ds_write2_b32 v149, v24, v28 offset1:16
	ds_write2_b32 v149, v25, v29 offset0:128 offset1:144
	ds_write2_b32 v148, v26, v30 offset1:16
	ds_write2_b32 v148, v27, v31 offset0:128 offset1:144
	ds_write2_b32 v149, v16, v20 offset0:32 offset1:48
	ds_write2_b32 v149, v17, v21 offset0:160 offset1:176
	ds_write2_b32 v148, v18, v22 offset0:32 offset1:48
	ds_write2_b32 v148, v19, v23 offset0:160 offset1:176
	ds_write2_b32 v149, v56, v60 offset0:64 offset1:80
	ds_write2_b32 v149, v57, v61 offset0:192 offset1:208
	ds_write2_b32 v148, v58, v62 offset0:64 offset1:80
	ds_write2_b32 v148, v59, v63 offset0:192 offset1:208
	ds_write2_b32 v149, v44, v72 offset0:96 offset1:112
	ds_write2_b32 v149, v45, v73 offset0:224 offset1:240
	ds_write2_b32 v148, v46, v74 offset0:96 offset1:112
	ds_write2_b32 v148, v47, v75 offset0:224 offset1:240
	ds_write2_b32 v147, v8, v12 offset1:16
	ds_write2_b32 v147, v9, v13 offset0:128 offset1:144
	ds_write2_b32 v146, v10, v14 offset1:16
	ds_write2_b32 v146, v11, v15 offset0:128 offset1:144
	ds_write2_b32 v147, v0, v4 offset0:32 offset1:48
	ds_write2_b32 v147, v1, v5 offset0:160 offset1:176
	ds_write2_b32 v146, v2, v6 offset0:32 offset1:48
	ds_write2_b32 v146, v3, v7 offset0:160 offset1:176
	ds_write2_b32 v147, v48, v64 offset0:64 offset1:80
	ds_write2_b32 v147, v49, v65 offset0:192 offset1:208
	ds_write2_b32 v146, v50, v66 offset0:64 offset1:80
	ds_write2_b32 v146, v51, v67 offset0:192 offset1:208
	ds_write2_b32 v147, v68, v76 offset0:96 offset1:112
	ds_write2_b32 v147, v69, v77 offset0:224 offset1:240
	ds_write2_b32 v146, v70, v78 offset0:96 offset1:112
	ds_write2_b32 v146, v71, v79 offset0:224 offset1:240
.LBB0_1146:
	s_or_b64 exec, exec, s[10:11]
	s_mul_hi_i32 s2, s13, 0x3e0f83e1
	s_lshr_b32 s3, s2, 31
	s_ashr_i32 s2, s2, 3
	s_add_i32 s2, s2, s3
	s_mul_hi_i32 s3, s2, 0x6000
	s_mulk_i32 s2, 0x6000
	s_add_u32 s2, s14, s2
	s_addc_u32 s3, s15, s3
	s_add_u32 s10, s2, 0x5000
	v_or_b32_e32 v136, s12, v143
	s_addc_u32 s11, s3, 0
	v_lshlrev_b32_e32 v132, 2, v136
	s_waitcnt lgkmcnt(0)
	s_barrier
	global_load_dwordx4 v[128:131], v132, s[10:11] offset:16
	s_nop 0
	global_load_dwordx4 v[132:135], v132, s[10:11]
	v_add_u32_e32 v137, s18, v144
	s_load_dwordx2 s[24:25], s[0:1], 0xe8
	v_lshlrev_b32_e32 v176, 2, v136
	v_lshrrev_b32_e32 v249, 13, v137
	v_min_u32_e32 v249, 1, v249
	v_lshlrev_b32_e32 v249, 8, v249
	v_sub_u32_e32 v249, v137, v249
	v_lshlrev_b32_e32 v249, 12, v249
	v_lshl_add_u32 v249, v136, 2, v249
	v_add_u32_e32 v248, 0x10000, v145
	s_waitcnt lgkmcnt(0)
	s_add_u32 s26, s24, 0x80000
	s_addc_u32 s27, s25, 0
	v_mov_b32_e32 v254, v249
	v_add_u32_e32 v253, 0x20000, v249
	v_add_u32_e32 v251, 0x40000, v249
	v_add_u32_e32 v250, 0x60000, v249
	global_load_dwordx4 v[138:141], v254, s[24:25]
	global_load_dwordx4 v[154:157], v254, s[24:25] offset:16
	global_load_dwordx4 v[158:161], v253, s[24:25]
	global_load_dwordx4 v[162:165], v253, s[24:25] offset:16
	global_load_dwordx4 v[166:169], v251, s[24:25]
	global_load_dwordx4 v[170:173], v251, s[24:25] offset:16
	global_load_dwordx4 v[178:181], v250, s[24:25]
	global_load_dwordx4 v[182:185], v250, s[24:25] offset:16
	global_load_dwordx4 v[186:189], v254, s[26:27]
	global_load_dwordx4 v[192:195], v254, s[26:27] offset:16
	global_load_dwordx4 v[198:201], v253, s[26:27]
	global_load_dwordx4 v[204:207], v253, s[26:27] offset:16
	global_load_dwordx4 v[208:211], v251, s[26:27]
	global_load_dwordx4 v[212:215], v251, s[26:27] offset:16
	global_load_dwordx4 v[216:219], v250, s[26:27]
	global_load_dwordx4 v[220:223], v250, s[26:27] offset:16
	ds_read_b128 v[224:227], v145
	ds_read_b128 v[228:231], v145 offset:16
	ds_read_b128 v[232:235], v145 offset:16384
	ds_read_b128 v[236:239], v145 offset:16400
	s_waitcnt vmcnt(14)
	v_pk_mul_f32 v[140:141], v[140:141], s[34:35] op_sel_hi:[1,0]
	v_pk_mul_f32 v[138:139], v[138:139], s[34:35] op_sel_hi:[1,0]
	v_pk_mul_f32 v[156:157], v[156:157], s[34:35] op_sel_hi:[1,0]
	v_pk_mul_f32 v[154:155], v[154:155], s[34:35] op_sel_hi:[1,0]
	s_waitcnt lgkmcnt(2)
	v_pk_fma_f32 v[140:141], v[134:135], v[226:227], v[140:141]
	v_pk_fma_f32 v[138:139], v[132:133], v[224:225], v[138:139]
	v_pk_fma_f32 v[156:157], v[130:131], v[230:231], v[156:157]
	v_pk_fma_f32 v[154:155], v[128:129], v[228:229], v[154:155]
	ds_read_b128 v[224:227], v145 offset:32768
	ds_read_b128 v[228:231], v145 offset:32784
	global_store_dwordx4 v254, v[138:141], s[24:25]
	global_store_dwordx4 v254, v[154:157], s[24:25] offset:16
	s_waitcnt vmcnt(14)
	v_pk_mul_f32 v[160:161], v[160:161], s[34:35] op_sel_hi:[1,0]
	v_pk_mul_f32 v[158:159], v[158:159], s[34:35] op_sel_hi:[1,0]
	v_pk_mul_f32 v[164:165], v[164:165], s[34:35] op_sel_hi:[1,0]
	v_pk_mul_f32 v[162:163], v[162:163], s[34:35] op_sel_hi:[1,0]
	s_waitcnt lgkmcnt(2)
	v_pk_fma_f32 v[160:161], v[134:135], v[234:235], v[160:161]
	v_pk_fma_f32 v[158:159], v[132:133], v[232:233], v[158:159]
	v_pk_fma_f32 v[164:165], v[130:131], v[238:239], v[164:165]
	v_pk_fma_f32 v[162:163], v[128:129], v[236:237], v[162:163]
	ds_read_b128 v[232:235], v145 offset:49152
	ds_read_b128 v[236:239], v145 offset:49168
	global_store_dwordx4 v253, v[158:161], s[24:25]
	global_store_dwordx4 v253, v[162:165], s[24:25] offset:16
	s_waitcnt vmcnt(14)
	v_pk_mul_f32 v[168:169], v[168:169], s[34:35] op_sel_hi:[1,0]
	v_pk_mul_f32 v[166:167], v[166:167], s[34:35] op_sel_hi:[1,0]
	v_pk_mul_f32 v[172:173], v[172:173], s[34:35] op_sel_hi:[1,0]
	v_pk_mul_f32 v[170:171], v[170:171], s[34:35] op_sel_hi:[1,0]
	s_waitcnt lgkmcnt(2)
	v_pk_fma_f32 v[168:169], v[134:135], v[226:227], v[168:169]
	v_pk_fma_f32 v[166:167], v[132:133], v[224:225], v[166:167]
	v_pk_fma_f32 v[172:173], v[130:131], v[230:231], v[172:173]
	v_pk_fma_f32 v[170:171], v[128:129], v[228:229], v[170:171]
	ds_read_b128 v[224:227], v248
	ds_read_b128 v[228:231], v248 offset:16
	global_store_dwordx4 v251, v[166:169], s[24:25]
	global_store_dwordx4 v251, v[170:173], s[24:25] offset:16
	s_waitcnt vmcnt(14)
	v_pk_mul_f32 v[180:181], v[180:181], s[34:35] op_sel_hi:[1,0]
	v_pk_mul_f32 v[178:179], v[178:179], s[34:35] op_sel_hi:[1,0]
	v_pk_mul_f32 v[184:185], v[184:185], s[34:35] op_sel_hi:[1,0]
	v_pk_mul_f32 v[182:183], v[182:183], s[34:35] op_sel_hi:[1,0]
	s_waitcnt lgkmcnt(2)
	v_pk_fma_f32 v[180:181], v[134:135], v[234:235], v[180:181]
	v_pk_fma_f32 v[178:179], v[132:133], v[232:233], v[178:179]
	v_pk_fma_f32 v[184:185], v[130:131], v[238:239], v[184:185]
	v_pk_fma_f32 v[182:183], v[128:129], v[236:237], v[182:183]
	ds_read_b128 v[232:235], v248 offset:16384
	ds_read_b128 v[236:239], v248 offset:16400
	global_store_dwordx4 v250, v[178:181], s[24:25]
	global_store_dwordx4 v250, v[182:185], s[24:25] offset:16
	s_waitcnt vmcnt(14)
	v_pk_mul_f32 v[188:189], v[188:189], s[34:35] op_sel_hi:[1,0]
	v_pk_mul_f32 v[186:187], v[186:187], s[34:35] op_sel_hi:[1,0]
	v_pk_mul_f32 v[194:195], v[194:195], s[34:35] op_sel_hi:[1,0]
	v_pk_mul_f32 v[192:193], v[192:193], s[34:35] op_sel_hi:[1,0]
	s_waitcnt lgkmcnt(2)
	v_pk_fma_f32 v[188:189], v[134:135], v[226:227], v[188:189]
	v_pk_fma_f32 v[186:187], v[132:133], v[224:225], v[186:187]
	v_pk_fma_f32 v[194:195], v[130:131], v[230:231], v[194:195]
	v_pk_fma_f32 v[192:193], v[128:129], v[228:229], v[192:193]
	ds_read_b128 v[224:227], v248 offset:32768
	ds_read_b128 v[228:231], v248 offset:32784
	global_store_dwordx4 v254, v[186:189], s[26:27]
	global_store_dwordx4 v254, v[192:195], s[26:27] offset:16
	s_waitcnt vmcnt(14)
	v_pk_mul_f32 v[200:201], v[200:201], s[34:35] op_sel_hi:[1,0]
	v_pk_mul_f32 v[198:199], v[198:199], s[34:35] op_sel_hi:[1,0]
	v_pk_mul_f32 v[206:207], v[206:207], s[34:35] op_sel_hi:[1,0]
	v_pk_mul_f32 v[204:205], v[204:205], s[34:35] op_sel_hi:[1,0]
	s_waitcnt lgkmcnt(2)
	v_pk_fma_f32 v[200:201], v[134:135], v[234:235], v[200:201]
	v_pk_fma_f32 v[198:199], v[132:133], v[232:233], v[198:199]
	v_pk_fma_f32 v[206:207], v[130:131], v[238:239], v[206:207]
	v_pk_fma_f32 v[204:205], v[128:129], v[236:237], v[204:205]
	ds_read_b128 v[232:235], v248 offset:49152
	ds_read_b128 v[236:239], v248 offset:49168
	global_store_dwordx4 v253, v[198:201], s[26:27]
	global_store_dwordx4 v253, v[204:207], s[26:27] offset:16
	s_waitcnt vmcnt(14)
	v_pk_mul_f32 v[210:211], v[210:211], s[34:35] op_sel_hi:[1,0]
	v_pk_mul_f32 v[208:209], v[208:209], s[34:35] op_sel_hi:[1,0]
	v_pk_mul_f32 v[214:215], v[214:215], s[34:35] op_sel_hi:[1,0]
	v_pk_mul_f32 v[212:213], v[212:213], s[34:35] op_sel_hi:[1,0]
	s_waitcnt lgkmcnt(2)
	v_pk_fma_f32 v[210:211], v[134:135], v[226:227], v[210:211]
	v_pk_fma_f32 v[208:209], v[132:133], v[224:225], v[208:209]
	v_pk_fma_f32 v[214:215], v[130:131], v[230:231], v[214:215]
	v_pk_fma_f32 v[212:213], v[128:129], v[228:229], v[212:213]
	global_store_dwordx4 v251, v[208:211], s[26:27]
	global_store_dwordx4 v251, v[212:215], s[26:27] offset:16
	s_waitcnt vmcnt(14)
	v_pk_mul_f32 v[218:219], v[218:219], s[34:35] op_sel_hi:[1,0]
	v_pk_mul_f32 v[216:217], v[216:217], s[34:35] op_sel_hi:[1,0]
	v_pk_mul_f32 v[222:223], v[222:223], s[34:35] op_sel_hi:[1,0]
	v_pk_mul_f32 v[220:221], v[220:221], s[34:35] op_sel_hi:[1,0]
	s_waitcnt lgkmcnt(0)
	v_pk_fma_f32 v[218:219], v[134:135], v[234:235], v[218:219]
	v_pk_fma_f32 v[216:217], v[132:133], v[232:233], v[216:217]
	v_pk_fma_f32 v[222:223], v[130:131], v[238:239], v[222:223]
	v_pk_fma_f32 v[220:221], v[128:129], v[236:237], v[220:221]
	global_store_dwordx4 v250, v[216:219], s[26:27]
	global_store_dwordx4 v250, v[220:223], s[26:27] offset:16

.LBB0_1158:
	s_or_b64 exec, exec, s[2:3]
	v_lshl_or_b32 v4, v136, 2, v191
	s_waitcnt lgkmcnt(0)
	s_barrier
	global_load_dwordx4 v[0:3], v4, s[10:11] offset:16
	s_nop 0
	global_load_dwordx4 v[4:7], v4, s[10:11]
	s_load_dwordx2 s[24:25], s[0:1], 0xe8
	v_lshlrev_b32_e32 v176, 2, v136
	v_lshrrev_b32_e32 v249, 13, v137
	v_min_u32_e32 v249, 1, v249
	v_lshlrev_b32_e32 v249, 8, v249
	v_sub_u32_e32 v249, v137, v249
	v_lshlrev_b32_e32 v249, 12, v249
	v_lshl_add_u32 v249, v136, 2, v249
	v_add_u32_e32 v248, 0x10000, v145
	s_waitcnt lgkmcnt(0)
	s_add_u32 s26, s24, 0x80000
	s_addc_u32 s27, s25, 0
	v_mov_b32_e32 v254, v249
	v_add_u32_e32 v253, 0x20000, v249
	v_add_u32_e32 v251, 0x40000, v249
	v_add_u32_e32 v250, 0x60000, v249
	global_load_dwordx4 v[8:11], v254, s[24:25] offset:512
	global_load_dwordx4 v[12:15], v254, s[24:25] offset:528
	global_load_dwordx4 v[16:19], v253, s[24:25] offset:512
	global_load_dwordx4 v[20:23], v253, s[24:25] offset:528
	global_load_dwordx4 v[24:27], v251, s[24:25] offset:512
	global_load_dwordx4 v[170:173], v251, s[24:25] offset:528
	global_load_dwordx4 v[178:181], v250, s[24:25] offset:512
	global_load_dwordx4 v[182:185], v250, s[24:25] offset:528
	global_load_dwordx4 v[186:189], v254, s[26:27] offset:512
	global_load_dwordx4 v[192:195], v254, s[26:27] offset:528
	global_load_dwordx4 v[198:201], v253, s[26:27] offset:512
	global_load_dwordx4 v[204:207], v253, s[26:27] offset:528
	global_load_dwordx4 v[208:211], v251, s[26:27] offset:512
	global_load_dwordx4 v[212:215], v251, s[26:27] offset:528
	global_load_dwordx4 v[216:219], v250, s[26:27] offset:512
	global_load_dwordx4 v[220:223], v250, s[26:27] offset:528
	ds_read_b128 v[224:227], v145
	ds_read_b128 v[228:231], v145 offset:16
	ds_read_b128 v[232:235], v145 offset:16384
	ds_read_b128 v[236:239], v145 offset:16400
	s_waitcnt vmcnt(14)
	v_pk_mul_f32 v[10:11], v[10:11], s[34:35] op_sel_hi:[1,0]
	v_pk_mul_f32 v[8:9], v[8:9], s[34:35] op_sel_hi:[1,0]
	v_pk_mul_f32 v[14:15], v[14:15], s[34:35] op_sel_hi:[1,0]
	v_pk_mul_f32 v[12:13], v[12:13], s[34:35] op_sel_hi:[1,0]
	s_waitcnt lgkmcnt(2)
	v_pk_fma_f32 v[10:11], v[6:7], v[226:227], v[10:11]
	v_pk_fma_f32 v[8:9], v[4:5], v[224:225], v[8:9]
	v_pk_fma_f32 v[14:15], v[2:3], v[230:231], v[14:15]
	v_pk_fma_f32 v[12:13], v[0:1], v[228:229], v[12:13]
	ds_read_b128 v[224:227], v145 offset:32768
	ds_read_b128 v[228:231], v145 offset:32784
	global_store_dwordx4 v254, v[8:11], s[24:25] offset:512
	global_store_dwordx4 v254, v[12:15], s[24:25] offset:528
	s_waitcnt vmcnt(14)
	v_pk_mul_f32 v[18:19], v[18:19], s[34:35] op_sel_hi:[1,0]
	v_pk_mul_f32 v[16:17], v[16:17], s[34:35] op_sel_hi:[1,0]
	v_pk_mul_f32 v[22:23], v[22:23], s[34:35] op_sel_hi:[1,0]
	v_pk_mul_f32 v[20:21], v[20:21], s[34:35] op_sel_hi:[1,0]
	s_waitcnt lgkmcnt(2)
	v_pk_fma_f32 v[18:19], v[6:7], v[234:235], v[18:19]
	v_pk_fma_f32 v[16:17], v[4:5], v[232:233], v[16:17]
	v_pk_fma_f32 v[22:23], v[2:3], v[238:239], v[22:23]
	v_pk_fma_f32 v[20:21], v[0:1], v[236:237], v[20:21]
	ds_read_b128 v[232:235], v145 offset:49152
	ds_read_b128 v[236:239], v145 offset:49168
	global_store_dwordx4 v253, v[16:19], s[24:25] offset:512
	global_store_dwordx4 v253, v[20:23], s[24:25] offset:528
	s_waitcnt vmcnt(14)
	v_pk_mul_f32 v[26:27], v[26:27], s[34:35] op_sel_hi:[1,0]
	v_pk_mul_f32 v[24:25], v[24:25], s[34:35] op_sel_hi:[1,0]
	v_pk_mul_f32 v[172:173], v[172:173], s[34:35] op_sel_hi:[1,0]
	v_pk_mul_f32 v[170:171], v[170:171], s[34:35] op_sel_hi:[1,0]
	s_waitcnt lgkmcnt(2)
	v_pk_fma_f32 v[26:27], v[6:7], v[226:227], v[26:27]
	v_pk_fma_f32 v[24:25], v[4:5], v[224:225], v[24:25]
	v_pk_fma_f32 v[172:173], v[2:3], v[230:231], v[172:173]
	v_pk_fma_f32 v[170:171], v[0:1], v[228:229], v[170:171]
	ds_read_b128 v[224:227], v248
	ds_read_b128 v[228:231], v248 offset:16
	global_store_dwordx4 v251, v[24:27], s[24:25] offset:512
	global_store_dwordx4 v251, v[170:173], s[24:25] offset:528
	s_waitcnt vmcnt(14)
	v_pk_mul_f32 v[180:181], v[180:181], s[34:35] op_sel_hi:[1,0]
	v_pk_mul_f32 v[178:179], v[178:179], s[34:35] op_sel_hi:[1,0]
	v_pk_mul_f32 v[184:185], v[184:185], s[34:35] op_sel_hi:[1,0]
	v_pk_mul_f32 v[182:183], v[182:183], s[34:35] op_sel_hi:[1,0]
	s_waitcnt lgkmcnt(2)
	v_pk_fma_f32 v[180:181], v[6:7], v[234:235], v[180:181]
	v_pk_fma_f32 v[178:179], v[4:5], v[232:233], v[178:179]
	v_pk_fma_f32 v[184:185], v[2:3], v[238:239], v[184:185]
	v_pk_fma_f32 v[182:183], v[0:1], v[236:237], v[182:183]
	ds_read_b128 v[232:235], v248 offset:16384
	ds_read_b128 v[236:239], v248 offset:16400
	global_store_dwordx4 v250, v[178:181], s[24:25] offset:512
	global_store_dwordx4 v250, v[182:185], s[24:25] offset:528
	s_waitcnt vmcnt(14)
	v_pk_mul_f32 v[188:189], v[188:189], s[34:35] op_sel_hi:[1,0]
	v_pk_mul_f32 v[186:187], v[186:187], s[34:35] op_sel_hi:[1,0]
	v_pk_mul_f32 v[194:195], v[194:195], s[34:35] op_sel_hi:[1,0]
	v_pk_mul_f32 v[192:193], v[192:193], s[34:35] op_sel_hi:[1,0]
	s_waitcnt lgkmcnt(2)
	v_pk_fma_f32 v[188:189], v[6:7], v[226:227], v[188:189]
	v_pk_fma_f32 v[186:187], v[4:5], v[224:225], v[186:187]
	v_pk_fma_f32 v[194:195], v[2:3], v[230:231], v[194:195]
	v_pk_fma_f32 v[192:193], v[0:1], v[228:229], v[192:193]
	ds_read_b128 v[224:227], v248 offset:32768
	ds_read_b128 v[228:231], v248 offset:32784
	global_store_dwordx4 v254, v[186:189], s[26:27] offset:512
	global_store_dwordx4 v254, v[192:195], s[26:27] offset:528
	s_waitcnt vmcnt(14)
	v_pk_mul_f32 v[200:201], v[200:201], s[34:35] op_sel_hi:[1,0]
	v_pk_mul_f32 v[198:199], v[198:199], s[34:35] op_sel_hi:[1,0]
	v_pk_mul_f32 v[206:207], v[206:207], s[34:35] op_sel_hi:[1,0]
	v_pk_mul_f32 v[204:205], v[204:205], s[34:35] op_sel_hi:[1,0]
	s_waitcnt lgkmcnt(2)
	v_pk_fma_f32 v[200:201], v[6:7], v[234:235], v[200:201]
	v_pk_fma_f32 v[198:199], v[4:5], v[232:233], v[198:199]
	v_pk_fma_f32 v[206:207], v[2:3], v[238:239], v[206:207]
	v_pk_fma_f32 v[204:205], v[0:1], v[236:237], v[204:205]
	ds_read_b128 v[232:235], v248 offset:49152
	ds_read_b128 v[236:239], v248 offset:49168
	global_store_dwordx4 v253, v[198:201], s[26:27] offset:512
	global_store_dwordx4 v253, v[204:207], s[26:27] offset:528
	s_waitcnt vmcnt(14)
	v_pk_mul_f32 v[210:211], v[210:211], s[34:35] op_sel_hi:[1,0]
	v_pk_mul_f32 v[208:209], v[208:209], s[34:35] op_sel_hi:[1,0]
	v_pk_mul_f32 v[214:215], v[214:215], s[34:35] op_sel_hi:[1,0]
	v_pk_mul_f32 v[212:213], v[212:213], s[34:35] op_sel_hi:[1,0]
	s_waitcnt lgkmcnt(2)
	v_pk_fma_f32 v[210:211], v[6:7], v[226:227], v[210:211]
	v_pk_fma_f32 v[208:209], v[4:5], v[224:225], v[208:209]
	v_pk_fma_f32 v[214:215], v[2:3], v[230:231], v[214:215]
	v_pk_fma_f32 v[212:213], v[0:1], v[228:229], v[212:213]
	global_store_dwordx4 v251, v[208:211], s[26:27] offset:512
	global_store_dwordx4 v251, v[212:215], s[26:27] offset:528
	s_waitcnt vmcnt(14)
	v_pk_mul_f32 v[218:219], v[218:219], s[34:35] op_sel_hi:[1,0]
	v_pk_mul_f32 v[216:217], v[216:217], s[34:35] op_sel_hi:[1,0]
	v_pk_mul_f32 v[222:223], v[222:223], s[34:35] op_sel_hi:[1,0]
	v_pk_mul_f32 v[220:221], v[220:221], s[34:35] op_sel_hi:[1,0]
	s_waitcnt lgkmcnt(0)
	v_pk_fma_f32 v[218:219], v[6:7], v[234:235], v[218:219]
	v_pk_fma_f32 v[216:217], v[4:5], v[232:233], v[216:217]
	v_pk_fma_f32 v[222:223], v[2:3], v[238:239], v[222:223]
	v_pk_fma_f32 v[220:221], v[0:1], v[236:237], v[220:221]
	global_store_dwordx4 v250, v[216:219], s[26:27] offset:512
	global_store_dwordx4 v250, v[220:223], s[26:27] offset:528
	s_branch .LBB0_1139
